# safe2 + strategy 1 (waitcnt placement): removed 4 redundant inline-asm vmcnt(0) drains that precede the compiler's counted waits in the attention pass prologues
# speedup vs baseline: 1.0033x; 1.0025x over previous
; #define GAS __attribute__((address_space(1)))
; __device__ __forceinline__ float bf2f(unsigned short b) { return __uint_as_float(((unsigned)b) << 16); }
; template <bool GRPB> __device__ __forceinline__ void attn_pass(const float mbK, const float bmax2, const int pass, float* __restrict__ scr, bf16* __restrict__ mixrow, const float lam, const float* __restrict__ gsub, const float one_m_li, ...
;     ...
;   const float cL = __uint_as_float(__builtin_amdgcn_readfirstlane(__float_as_uint(tb2[0]))), cR = __uint_as_float(__builtin_amdgcn_readfirstlane(__float_as_uint(tb2[384])));
;   const int qw = __builtin_amdgcn_readfirstlane(q0seq + wid * 32), qpos = qw + r32;
;   float m_reg, l_reg = 0; bf16x8 qr[4]; f32x16 o[4];
; #pragma unroll
;   for (int d = 0; d < 4; ++d) o[d] = f32x16{};
;   const bf16* Qw = Qb + (long)(wid * 32 + r32) * LDK + hi * 8;
; #pragma unroll
;   for (int d0 = 0; d0 < 4; ++d0) qr[d0] = *(const GAS bf16x8*)(Qw + d0 * 16);
;   { float qs = 0.f;
; #pragma unroll
;     for (int d0 = 0; d0 < 4; ++d0)
; #pragma unroll
;       for (int j = 0; j < 8; ++j) { const float v = bf2f((unsigned short)qr[d0][j]); qs = fmaf(v, v, qs); }
; __device__ __forceinline__ void attn_phase(const Params& p, int e, char* lds) {
;     ...
;     const long row0 = (long)b * SEQ + qb * 256;
;     float bmax2 = -1e30f;
; #pragma unroll 4
;     for (int bk = 0; bk < 32; ++bk) bmax2 = fmaxf(bmax2, p.rel_bias[bk * 4 + h] * LOG2E);
;     const unsigned* kmx = (const unsigned*)(p.ws + WS_KMX) + e * 128 + b * 8 + h * 2;
;     const float mbK0 = __uint_as_float(__builtin_amdgcn_readfirstlane(__float_as_uint(C1 * 1.01f * __builtin_sqrtf(2.0f * __uint_as_float(kmx[0])))));
;     const float mbK1 = __uint_as_float(__builtin_amdgcn_readfirstlane(__float_as_uint(C1 * 1.01f * __builtin_sqrtf(2.0f * __uint_as_float(kmx[1])))));
;     bmax2 = __uint_as_float(__builtin_amdgcn_readfirstlane(__float_as_uint(bmax2)));
;     if (__builtin_amdgcn_readfirstlane(wid) & 1) {
.LBB0_295:
	s_lshl_b32 s0, s59, 8
	s_ashr_i32 s48, s59, 6
	s_and_b32 s39, s0, 0xf00
	s_ashr_i32 s49, s48, 31
	s_lshl_b32 s0, s48, 3
	s_lshl_b64 s[46:47], s[48:49], 12
	s_ashr_i32 s1, s0, 31
	s_or_b32 s46, s46, s39
	s_lshl_b64 s[0:1], s[0:1], 2
	s_add_u32 s0, s35, s0
	s_addc_u32 s1, s56, s1
	s_lshl_b32 s2, s44, 3
	s_add_u32 s0, s0, s2
	s_addc_u32 s1, s1, 0
	v_mov_b64_e32 v[2:3], s[0:1]
	flat_load_dwordx2 v[2:3], v[2:3]
	s_mov_b32 s2, 0xf800000
	v_mov_b32_e32 v6, 0x3fba82f9
	v_readfirstlane_b32 s45, v0
	v_lshrrev_b32_e32 v0, 6, v232
	s_mov_b32 s10, 0xf800000
	v_mov_b32_e32 v198, 0x260
	s_waitcnt vmcnt(0) lgkmcnt(0)
	v_add_f32_e32 v1, v2, v2
	v_cmp_gt_f32_e32 vcc, s2, v1
	v_mul_f32_e32 v2, 0x4f800000, v1
	s_nop 0
	v_cndmask_b32_e32 v1, v1, v2, vcc
	v_sqrt_f32_e32 v2, v1
	s_nop 0
	v_add_u32_e32 v4, -1, v2
	v_fma_f32 v5, -v4, v2, v1
	v_cmp_ge_f32_e64 s[0:1], 0, v5
	v_add_u32_e32 v5, 1, v2
	s_nop 0
	v_cndmask_b32_e64 v4, v2, v4, s[0:1]
	v_fma_f32 v2, -v5, v2, v1
	v_cmp_lt_f32_e64 s[0:1], 0, v2
	s_nop 1
	v_cndmask_b32_e64 v2, v4, v5, s[0:1]
	v_mul_f32_e32 v4, 0x37800000, v2
	v_mov_b32_e32 v5, 0x260
	v_cndmask_b32_e32 v2, v2, v4, vcc
	v_cmp_class_f32_e32 vcc, v1, v5
	s_nop 1
	v_cndmask_b32_e32 v1, v2, v1, vcc
	s_nop 0
	v_readfirstlane_b32 s0, v1
	v_add_f32_e32 v1, v3, v3
	v_cmp_gt_f32_e32 vcc, s2, v1
	v_mul_f32_e32 v2, 0x4f800000, v1
	v_mul_f32_e32 v216, s0, v6
	v_cndmask_b32_e32 v1, v1, v2, vcc
	v_sqrt_f32_e32 v2, v1
	s_nop 0
	v_add_u32_e32 v3, -1, v2
	v_fma_f32 v4, -v3, v2, v1
	v_cmp_ge_f32_e64 s[0:1], 0, v4
	v_add_u32_e32 v4, 1, v2
	s_nop 0
	v_cndmask_b32_e64 v3, v2, v3, s[0:1]
	v_fma_f32 v2, -v4, v2, v1
	v_cmp_lt_f32_e64 s[0:1], 0, v2
	s_nop 1
	v_cndmask_b32_e64 v2, v3, v4, s[0:1]
	v_mul_f32_e32 v3, 0x37800000, v2
	v_cndmask_b32_e32 v2, v2, v3, vcc
	v_cmp_class_f32_e32 vcc, v1, v5
	s_nop 1
	v_cndmask_b32_e32 v1, v2, v1, vcc
	s_nop 0
	v_readfirstlane_b32 s0, v1
	s_nop 1
	v_mul_f32_e32 v214, s0, v6
	v_readfirstlane_b32 s0, v0
	s_bitcmp1_b32 s0, 0
	s_cselect_b64 s[20:21], -1, 0
	s_lshl_b64 s[0:1], s[46:47], 13
	s_add_u32 s0, s30, s0
	s_addc_u32 s1, s31, s1
	s_lshl_b32 s2, s44, 8
	s_add_u32 s52, s0, s2
	s_addc_u32 s53, s1, 0
	s_lshl_b64 s[48:49], s[48:49], 25
	s_add_u32 s0, s30, s48
	s_addc_u32 s1, s31, s49
	s_add_u32 s50, s0, s2
	s_addc_u32 s51, s1, 0
	s_mov_b64 s[0:1], -1
	s_and_b64 vcc, exec, s[20:21]
	s_cbranch_vccz .LBB0_347
	v_readlane_b32 s0, v254, 39
	v_mov_b32_e32 v146, v232
	v_mov_b32_e32 v201, v144
	v_mov_b32_e32 v0, s0
	ds_read_b32 v0, v0
	v_readlane_b32 s0, v254, 40
	v_lshrrev_b32_e32 v2, 1, v146
	v_and_b32_e32 v200, 16, v2
	v_lshlrev_b32_e32 v8, 4, v146
	s_waitcnt lgkmcnt(0)
	v_readfirstlane_b32 s61, v0
	v_mov_b32_e32 v0, s0
	ds_read_b32 v0, v0
	s_movk_i32 s0, 0xffe0
	v_and_b32_e32 v9, 48, v8
	v_ashrrev_i32_e32 v12, 3, v146
	v_ashrrev_i32_e32 v13, 31, v12
	s_waitcnt lgkmcnt(0)
	v_readfirstlane_b32 s62, v0
	v_ashrrev_i32_e32 v0, 1, v146
	v_and_b32_e32 v1, 0xffffffe0, v0
	v_add_u32_e32 v1, s39, v1
	v_bfi_b32 v0, s0, v0, v146
	v_readfirstlane_b32 s63, v1
	v_ashrrev_i32_e32 v1, 31, v0
	v_lshlrev_b64 v[0:1], 13, v[0:1]
	v_lshl_add_u64 v[0:1], s[52:53], 0, v[0:1]
	v_lshl_add_u64 v[0:1], v[0:1], 0, v[200:201]
	global_load_dwordx4 v[164:167], v[0:1], off
	global_load_dwordx4 v[160:163], v[0:1], off offset:32
	global_load_dwordx4 v[156:159], v[0:1], off offset:64
	global_load_dwordx4 v[152:155], v[0:1], off offset:96
	s_barrier
	v_lshlrev_b64 v[52:53], 13, v[12:13]
	v_mov_b32_e32 v11, v144
	v_and_b32_e32 v147, 31, v146
	v_add_u32_e32 v215, s63, v147
	s_waitcnt vmcnt(3)
	v_lshlrev_b32_e32 v0, 16, v164
	v_fma_f32 v0, v0, v0, 0
	v_and_b32_e32 v1, 0xffff0000, v164
	v_fmac_f32_e32 v0, v1, v1
	v_lshlrev_b32_e32 v1, 16, v165
	v_fmac_f32_e32 v0, v1, v1
	v_and_b32_e32 v1, 0xffff0000, v165
	v_fmac_f32_e32 v0, v1, v1
	v_lshlrev_b32_e32 v1, 16, v166
	v_fmac_f32_e32 v0, v1, v1
	v_and_b32_e32 v1, 0xffff0000, v166
	v_fmac_f32_e32 v0, v1, v1
	v_lshlrev_b32_e32 v1, 16, v167
	v_fmac_f32_e32 v0, v1, v1
	v_and_b32_e32 v1, 0xffff0000, v167
	v_fmac_f32_e32 v0, v1, v1
	s_waitcnt vmcnt(2)
	v_lshlrev_b32_e32 v1, 16, v160
	v_fmac_f32_e32 v0, v1, v1
	v_and_b32_e32 v1, 0xffff0000, v160
	v_fmac_f32_e32 v0, v1, v1
	v_lshlrev_b32_e32 v1, 16, v161
	v_fmac_f32_e32 v0, v1, v1
	v_and_b32_e32 v1, 0xffff0000, v161
	v_fmac_f32_e32 v0, v1, v1
	v_lshlrev_b32_e32 v1, 16, v162
	v_fmac_f32_e32 v0, v1, v1
	v_and_b32_e32 v1, 0xffff0000, v162
	v_fmac_f32_e32 v0, v1, v1
	v_lshlrev_b32_e32 v1, 16, v163
	v_fmac_f32_e32 v0, v1, v1
	v_and_b32_e32 v1, 0xffff0000, v163
	v_fmac_f32_e32 v0, v1, v1
	s_waitcnt vmcnt(1)
	v_lshlrev_b32_e32 v1, 16, v156
	v_fmac_f32_e32 v0, v1, v1
	v_and_b32_e32 v1, 0xffff0000, v156
	v_fmac_f32_e32 v0, v1, v1
	v_lshlrev_b32_e32 v1, 16, v157
	v_fmac_f32_e32 v0, v1, v1
	v_and_b32_e32 v1, 0xffff0000, v157
	v_fmac_f32_e32 v0, v1, v1
	v_lshlrev_b32_e32 v1, 16, v158
	v_fmac_f32_e32 v0, v1, v1
	v_and_b32_e32 v1, 0xffff0000, v158
	v_fmac_f32_e32 v0, v1, v1
	v_lshlrev_b32_e32 v1, 16, v159
	v_fmac_f32_e32 v0, v1, v1
	v_and_b32_e32 v1, 0xffff0000, v159
	v_fmac_f32_e32 v0, v1, v1
	s_waitcnt vmcnt(0)
; __device__ __forceinline__ int v_st(int k, int c) { const int kk = (k & ~0xC) | ((k & 4) << 1) | ((k & 8) >> 1); return ((kk >> 3) * 4 + (c >> 5)) * 512 + ((kk & 7) * 32 + (c & 31)) * 2; }
; __device__ __forceinline__ int v_rd_base(int lane) { return ((lane & 3) << 3) | (((lane >> 2) & 3) << 6) | (((lane >> 4) & 1) << 5) | (((lane >> 5) & 1) << 8); }
; #define SLOAD(i, k0) do { sr_[i].vs0 = *(const GAS bf16x8*)(&Vh[(long)((k0) + sr) * LDK + sc]); sr_[i].vs1 = *(const GAS bf16x8*)(&Vh[(long)((k0) + 32 + sr) * LDK + sc]); \
;     sr_[i].ks0 = *(const GAS bf16x8*)(&Kh[(long)((k0) + kr) * LDK + kc]); } while (0)
; #define SWRITE(b, i) do { *(bf16x8*)(V_lds + (b) * SHM_V + vst0) = sr_[i].vs0; *(bf16x8*)(V_lds + (b) * SHM_V + vst1) = sr_[i].vs1; \
;     *(bf16x8*)(K_lds + (b) * SHM_K + kst) = sr_[i].ks0; } while (0)
; template <bool GRPB> __device__ __forceinline__ void attn_pass(const float mbK, const float bmax2, const int pass, float* __restrict__ scr, bf16* __restrict__ mixrow, const float lam, const float* __restrict__ gsub, const float one_m_li, ...
;     ...
;     { auto rr = __builtin_amdgcn_permlane32_swap(__float_as_uint(qs), __float_as_uint(qs), false, false); qs = __uint_as_float(rr[0]) + __uint_as_float(rr[1]); }
;     m_reg = __builtin_sqrtf(qs) * mbK + bmax2 + 0.25f; }
;   const int sr = tid >> 4, sc = (tid & 15) * 8, vst0 = v_st(sr, sc), vst1 = v_st(32 + sr, sc);
;   const int kr = tid >> 3, kc = (tid & 7) * 8, kst = KSWZ64(kr, kc * 2);
;   const int vb0 = (int)(uintptr_t)V_lds + v_rd_base(lane);
;   struct { bf16x8 vs0, vs1, ks0; } sr_[2];
;     ...
;   f32x16 pA0, pA1, pB0, pB1; float mnA, mnB, alA, alB; bf16x8 pa0, pa1, pa2, pa3; constexpr int NT = SEQ / KVBLK;
;   __syncthreads();
;   SLOAD(0, 0); SLOAD(1, KVBLK); asm volatile("s_waitcnt vmcnt(0)" ::: "memory"); SWRITE(0, 0); SWRITE(1, 1);
;   SLOAD(0, 2 * KVBLK); asm volatile("s_waitcnt vmcnt(0)" ::: "memory"); SWRITE(2, 0); __syncthreads();
	v_lshlrev_b32_e32 v1, 16, v152
	v_fmac_f32_e32 v0, v1, v1
	v_and_b32_e32 v1, 0xffff0000, v152
	v_fmac_f32_e32 v0, v1, v1
	v_lshlrev_b32_e32 v1, 16, v153
	v_fmac_f32_e32 v0, v1, v1
	v_and_b32_e32 v1, 0xffff0000, v153
	v_fmac_f32_e32 v0, v1, v1
	v_lshlrev_b32_e32 v1, 16, v154
	v_fmac_f32_e32 v0, v1, v1
	v_and_b32_e32 v1, 0xffff0000, v154
	v_fmac_f32_e32 v0, v1, v1
	v_lshlrev_b32_e32 v1, 16, v155
	v_fmac_f32_e32 v0, v1, v1
	v_and_b32_e32 v1, 0xffff0000, v155
	v_fmac_f32_e32 v0, v1, v1
	v_mov_b32_e32 v1, v0
	s_nop 1
	v_permlane32_swap_b32_e32 v0, v1
	v_add_f32_e32 v0, v0, v1
	v_cmp_gt_f32_e32 vcc, s10, v0
	v_mul_f32_e32 v1, 0x4f800000, v0
	s_nop 0
	v_cndmask_b32_e32 v0, v0, v1, vcc
	v_sqrt_f32_e32 v1, v0
	s_nop 0
	v_add_u32_e32 v2, -1, v1
	v_fma_f32 v3, -v2, v1, v0
	v_cmp_ge_f32_e64 s[0:1], 0, v3
	v_add_u32_e32 v3, 1, v1
	s_nop 0
	v_cndmask_b32_e64 v2, v1, v2, s[0:1]
	v_fma_f32 v1, -v3, v1, v0
	v_cmp_lt_f32_e64 s[0:1], 0, v1
	s_nop 1
	v_cndmask_b32_e64 v1, v2, v3, s[0:1]
	v_mul_f32_e32 v2, 0x37800000, v1
	v_cndmask_b32_e32 v1, v1, v2, vcc
	v_ashrrev_i32_e32 v2, 4, v146
	v_cmp_class_f32_e32 vcc, v0, v198
	v_and_b32_e32 v3, 0xfffff0, v2
	v_lshlrev_b32_e32 v5, 1, v2
	v_cndmask_b32_e32 v0, v1, v0, vcc
	v_lshlrev_b32_e32 v1, 3, v146
	v_and_or_b32 v3, v5, 8, v3
	v_lshrrev_b32_e32 v5, 1, v2
	v_lshrrev_b32_e32 v3, 1, v3
	v_bfe_u32 v7, v1, 5, 2
	v_and_b32_e32 v6, 3, v2
	v_or_b32_e32 v3, v3, v7
	v_and_or_b32 v5, v5, 4, v6
	v_lshlrev_b32_e32 v3, 9, v3
	v_lshlrev_b32_e32 v5, 6, v5
	v_add_u32_e32 v6, 32, v2
	v_or3_b32 v201, v3, v5, v9
	v_and_b32_e32 v3, 0xfffff0, v6
	v_lshlrev_b32_e32 v10, 1, v6
	v_and_or_b32 v3, v10, 8, v3
	v_lshrrev_b32_e32 v3, 1, v3
	v_or_b32_e32 v3, v3, v7
	v_lshlrev_b32_e32 v3, 9, v3
	v_or3_b32 v217, v3, v5, v9
	v_lshlrev_b32_e32 v3, 7, v12
	v_and_b32_e32 v10, 0x70, v8
	v_and_b32_e32 v5, 0x70, v146
	v_bitop3_b32 v218, v10, v3, v5 bitop3:0xde
	v_ashrrev_i32_e32 v3, 31, v2
	v_and_b32_e32 v4, 0x78, v1
	v_lshlrev_b64 v[50:51], 13, v[2:3]
	v_lshl_add_u64 v[2:3], s[50:51], 0, v[50:51]
	v_lshlrev_b32_e32 v8, 1, v4
	v_mov_b32_e32 v9, v144
	v_ashrrev_i32_e32 v7, 31, v6
	v_lshl_add_u64 v[18:19], v[2:3], 0, v[8:9]
	v_lshlrev_b64 v[6:7], 13, v[6:7]
	global_load_dwordx4 v[2:5], v[18:19], off offset:2048
	v_lshl_add_u64 v[6:7], s[50:51], 0, v[6:7]
	s_mov_b32 s0, 0x80000
	v_lshl_add_u64 v[6:7], v[6:7], 0, v[8:9]
	v_add_co_u32_e32 v14, vcc, s0, v18
	global_load_dwordx4 v[6:9], v[6:7], off offset:2048
	v_lshl_add_u64 v[12:13], s[50:51], 0, v[52:53]
	v_addc_co_u32_e32 v15, vcc, 0, v19, vcc
	s_mov_b32 s1, 0xc0000
	v_lshl_add_u64 v[20:21], v[12:13], 0, v[10:11]
	v_add_co_u32_e32 v22, vcc, s1, v18
	global_load_dwordx4 v[10:13], v[20:21], off offset:1024
	s_nop 0
	v_addc_co_u32_e32 v23, vcc, 0, v19, vcc
	global_load_dwordx4 v[14:17], v[14:15], off offset:2048
	v_add_co_u32_e32 v26, vcc, s0, v20
	global_load_dwordx4 v[22:25], v[22:23], off offset:2048
	s_nop 0
	v_addc_co_u32_e32 v27, vcc, 0, v21, vcc
	global_load_dwordx4 v[26:29], v[26:27], off offset:1024
	v_add_u32_e32 v30, 0, v201
	s_mov_b32 s0, 0x100000
	s_waitcnt vmcnt(3)
	v_add_u32_e32 v31, 0, v217
	s_mov_b32 s1, 0x140000
	v_add_u32_e32 v222, 0, v218
	v_and_b32_e32 v1, 0x70, v1
	v_fma_f32 v0, v216, v0, s45
	v_add_f32_e32 v0, 0x3e800000, v0
	s_waitcnt vmcnt(5)
	ds_write_b128 v30, v[2:5]
	v_add_co_u32_e32 v2, vcc, s0, v18
	s_waitcnt vmcnt(4)
	ds_write_b128 v31, v[6:9]
	v_addc_co_u32_e32 v3, vcc, 0, v19, vcc
	v_add_co_u32_e32 v6, vcc, s1, v18
	s_waitcnt vmcnt(3)
	ds_write_b128 v222, v[10:13] offset:49152
	v_addc_co_u32_e32 v7, vcc, 0, v19, vcc
	v_add_co_u32_e32 v10, vcc, s0, v20
	global_load_dwordx4 v[2:5], v[2:3], off offset:2048
	s_nop 0
	v_addc_co_u32_e32 v11, vcc, 0, v21, vcc
	global_load_dwordx4 v[6:9], v[6:7], off offset:2048
	s_nop 0
	global_load_dwordx4 v[10:13], v[10:11], off offset:1024
	s_waitcnt vmcnt(5)
	ds_write_b128 v30, v[14:17] offset:16384
	s_waitcnt vmcnt(4)
	ds_write_b128 v31, v[22:25] offset:16384
	s_waitcnt vmcnt(3)
	ds_write_b128 v222, v[26:29] offset:57344
	s_waitcnt vmcnt(2)
	ds_write_b128 v30, v[2:5] offset:32768
	s_waitcnt vmcnt(1)
	ds_write_b128 v31, v[6:9] offset:32768
	v_add_u32_e32 v2, 0x10000, v222
	s_waitcnt vmcnt(0)
	ds_write_b128 v2, v[10:13]
	v_lshlrev_b32_e32 v10, 7, v147
	v_or_b32_e32 v11, 32, v200
	v_bitop3_b32 v227, v11, v10, v1 bitop3:0xde
	v_or_b32_e32 v11, 64, v200
	v_bitop3_b32 v229, v11, v10, v1 bitop3:0xde
	v_or_b32_e32 v11, 0x60, v200
	v_bitop3_b32 v224, v200, v10, v1 bitop3:0xde
	v_bitop3_b32 v230, v11, v10, v1 bitop3:0xde
	v_add_u32_e32 v223, 0, v224
	v_add_u32_e32 v225, 0, v227
	v_add_u32_e32 v226, 0, v229
	v_add_u32_e32 v228, 0, v230
	s_waitcnt lgkmcnt(0)
	s_barrier
; #define SBAR() __builtin_amdgcn_sched_barrier(0)
; __device__ __forceinline__ void partialSM(f32x16& p0, f32x16& p1, float& m_reg, float& mn, float& alpha, int kt0, int qpos, int qw, int hi, const float* tb2, float cL, float cR) {
;   mn = m_reg; alpha = 1.f;
;   const int rel_hi = kt0 + 63 - qw, rel_lo = kt0 - (qw + 31);
;   if (rel_hi <= -91 || rel_lo >= 91) {
;     const float cm = ((rel_hi <= -91) ? cL : cR) - m_reg;
; #pragma unroll
;     for (int r = 0; r < 16; ++r) { p0[r] = fmaf(p0[r], C1, cm); p1[r] = fmaf(p1[r], C1, cm); }
;   } else {
;     const float* tp = tb2 + (kt0 - qpos + 192 + 4 * hi);
; #pragma unroll
;     for (int r4 = 0; r4 < 4; ++r4) {
;       float ta[4], tb[4];
; #pragma unroll
;       for (int i = 0; i < 4; ++i) { ta[i] = tp[8 * r4 + i] - m_reg; tb[i] = tp[32 + 8 * r4 + i] - m_reg; }
; #pragma unroll
;       for (int i = 0; i < 4; ++i) { p0[4 * r4 + i] = fmaf(p0[4 * r4 + i], C1, ta[i]); p1[4 * r4 + i] = fmaf(p1[4 * r4 + i], C1, tb[i]); }
;       asm volatile("" ::: "memory");
;     }
; __device__ __forceinline__ void qkt(f32x16& p0, f32x16& p1, const char* Ks, const bf16x8* qr, int r32, int hi) {
;   bf16x8 ka[4], kb[4];
; #pragma unroll
;   for (int d0 = 0; d0 < 4; ++d0) { const int cb = (d0 * 16 + hi * 8) * 2;
;     ka[d0] = *reinterpret_cast<const bf16x8*>(Ks + KSWZ64(r32, cb)); kb[d0] = *reinterpret_cast<const bf16x8*>(Ks + KSWZ64(32 + r32, cb)); }
;   asm volatile("s_waitcnt lgkmcnt(0)" ::: "memory"); SBAR();
;   p0 = f32x16{}; p1 = f32x16{};
; #pragma unroll
;   for (int d0 = 0; d0 < 4; ++d0) {
;     p0 = __builtin_amdgcn_mfma_f32_32x32x16_bf16(ka[d0], qr[d0], p0, 0, 0, 0);
;     p1 = __builtin_amdgcn_mfma_f32_32x32x16_bf16(kb[d0], qr[d0], p1, 0, 0, 0); }
	ds_read_b128 v[2:5], v223 offset:49152
	ds_read_b128 v[6:9], v223 offset:53248
	ds_read_b128 v[34:37], v225 offset:49152
	ds_read_b128 v[38:41], v225 offset:53248
	ds_read_b128 v[42:45], v226 offset:49152
	ds_read_b128 v[46:49], v226 offset:53248
	ds_read_b128 v[54:57], v228 offset:49152
	ds_read_b128 v[58:61], v228 offset:53248
	s_waitcnt lgkmcnt(0)
	s_waitcnt lgkmcnt(7)
	v_mfma_f32_32x32x16_bf16 v[18:33], v[2:5], v[164:167], 0
	s_add_i32 s2, s63, 0xffffff66
	s_mov_b64 s[0:1], -1
	s_cmp_gt_u32 s2, 0xfffffeec
	s_waitcnt lgkmcnt(6)
	v_mfma_f32_32x32x16_bf16 v[2:17], v[6:9], v[164:167], 0
	s_waitcnt lgkmcnt(5)
	v_mfma_f32_32x32x16_bf16 v[18:33], v[34:37], v[160:163], v[18:33]
	s_waitcnt lgkmcnt(4)
	v_mfma_f32_32x32x16_bf16 v[2:17], v[38:41], v[160:163], v[2:17]
	s_waitcnt lgkmcnt(3)
	v_mfma_f32_32x32x16_bf16 v[18:33], v[42:45], v[156:159], v[18:33]
	s_waitcnt lgkmcnt(2)
	v_mfma_f32_32x32x16_bf16 v[2:17], v[46:49], v[156:159], v[2:17]
	s_waitcnt lgkmcnt(1)
	v_mfma_f32_32x32x16_bf16 v[18:33], v[54:57], v[152:155], v[18:33]
	v_lshlrev_b32_e32 v54, 2, v215
	s_waitcnt lgkmcnt(0)
	v_mfma_f32_32x32x16_bf16 v[2:17], v[58:61], v[152:155], v[2:17]
	s_cbranch_scc0 .LBB0_298
	v_sub_u32_e32 v1, 0, v54
	s_mov_b32 s0, 0x12b00
	v_add3_u32 v1, v1, v200, s0
	ds_read2_b32 v[34:35], v1 offset1:1
	ds_read2_b32 v[56:57], v1 offset0:32 offset1:33
	ds_read2_b32 v[58:59], v1 offset0:34 offset1:35
	ds_read2_b32 v[36:37], v1 offset0:2 offset1:3
	ds_read2_b32 v[38:39], v1 offset0:8 offset1:9
	ds_read2_b32 v[60:61], v1 offset0:40 offset1:41
	ds_read2_b32 v[62:63], v1 offset0:42 offset1:43
	ds_read2_b32 v[40:41], v1 offset0:10 offset1:11
	ds_read2_b32 v[42:43], v1 offset0:16 offset1:17
	ds_read2_b32 v[64:65], v1 offset0:48 offset1:49
	ds_read2_b32 v[66:67], v1 offset0:50 offset1:51
	ds_read2_b32 v[44:45], v1 offset0:18 offset1:19
	ds_read2_b32 v[46:47], v1 offset0:24 offset1:25
	ds_read2_b32 v[48:49], v1 offset0:26 offset1:27
	ds_read2_b32 v[68:69], v1 offset0:58 offset1:59
	ds_read2_b32 v[70:71], v1 offset0:56 offset1:57
	s_waitcnt lgkmcnt(3)
	v_sub_f32_e32 v47, v47, v0
	v_sub_f32_e32 v46, v46, v0
	s_waitcnt lgkmcnt(2)
	v_sub_f32_e32 v49, v49, v0
	v_sub_f32_e32 v48, v48, v0
	v_sub_f32_e32 v43, v43, v0
	v_sub_f32_e32 v42, v42, v0
	v_sub_f32_e32 v45, v45, v0
	v_sub_f32_e32 v44, v44, v0
	v_sub_f32_e32 v39, v39, v0
	v_sub_f32_e32 v38, v38, v0
	v_sub_f32_e32 v41, v41, v0
	v_sub_f32_e32 v40, v40, v0
	v_sub_f32_e32 v35, v35, v0
	v_sub_f32_e32 v34, v34, v0
	v_sub_f32_e32 v37, v37, v0
	v_sub_f32_e32 v36, v36, v0
	s_waitcnt lgkmcnt(0)
	v_sub_f32_e32 v71, v71, v0
	v_sub_f32_e32 v70, v70, v0
	v_sub_f32_e32 v69, v69, v0
	v_sub_f32_e32 v68, v68, v0
	v_sub_f32_e32 v65, v65, v0
	v_sub_f32_e32 v64, v64, v0
	v_sub_f32_e32 v67, v67, v0
	v_sub_f32_e32 v66, v66, v0
	v_sub_f32_e32 v61, v61, v0
	v_sub_f32_e32 v60, v60, v0
	v_sub_f32_e32 v63, v63, v0
	v_sub_f32_e32 v62, v62, v0
	v_sub_f32_e32 v57, v57, v0
	v_sub_f32_e32 v56, v56, v0
	v_sub_f32_e32 v59, v59, v0
	v_sub_f32_e32 v58, v58, v0
	v_pk_fma_f32 v[36:37], v[20:21], s[6:7], v[36:37] op_sel_hi:[1,0,1]
	v_pk_fma_f32 v[34:35], v[18:19], s[6:7], v[34:35] op_sel_hi:[1,0,1]
	v_pk_fma_f32 v[40:41], v[24:25], s[6:7], v[40:41] op_sel_hi:[1,0,1]
	v_pk_fma_f32 v[38:39], v[22:23], s[6:7], v[38:39] op_sel_hi:[1,0,1]
	v_pk_fma_f32 v[44:45], v[28:29], s[6:7], v[44:45] op_sel_hi:[1,0,1]
	v_pk_fma_f32 v[42:43], v[26:27], s[6:7], v[42:43] op_sel_hi:[1,0,1]
	v_pk_fma_f32 v[48:49], v[32:33], s[6:7], v[48:49] op_sel_hi:[1,0,1]
	v_pk_fma_f32 v[46:47], v[30:31], s[6:7], v[46:47] op_sel_hi:[1,0,1]
	v_pk_fma_f32 v[82:83], v[4:5], s[6:7], v[58:59] op_sel_hi:[1,0,1]
	v_pk_fma_f32 v[80:81], v[2:3], s[6:7], v[56:57] op_sel_hi:[1,0,1]
	v_pk_fma_f32 v[86:87], v[8:9], s[6:7], v[62:63] op_sel_hi:[1,0,1]
	v_pk_fma_f32 v[84:85], v[6:7], s[6:7], v[60:61] op_sel_hi:[1,0,1]
	v_pk_fma_f32 v[90:91], v[12:13], s[6:7], v[66:67] op_sel_hi:[1,0,1]
	v_pk_fma_f32 v[88:89], v[10:11], s[6:7], v[64:65] op_sel_hi:[1,0,1]
	v_pk_fma_f32 v[94:95], v[16:17], s[6:7], v[68:69] op_sel_hi:[1,0,1]
	v_pk_fma_f32 v[92:93], v[14:15], s[6:7], v[70:71] op_sel_hi:[1,0,1]
	s_mov_b64 s[0:1], 0

; #define GAS __attribute__((address_space(1)))
; __device__ __forceinline__ float bf2f(unsigned short b) { return __uint_as_float(((unsigned)b) << 16); }
; template <bool GRPB> __device__ __forceinline__ void attn_pass(const float mbK, const float bmax2, const int pass, float* __restrict__ scr, bf16* __restrict__ mixrow, const float lam, const float* __restrict__ gsub, const float one_m_li, ...
;     ...
;   const float cL = __uint_as_float(__builtin_amdgcn_readfirstlane(__float_as_uint(tb2[0]))), cR = __uint_as_float(__builtin_amdgcn_readfirstlane(__float_as_uint(tb2[384])));
;   const int qw = __builtin_amdgcn_readfirstlane(q0seq + wid * 32), qpos = qw + r32;
;   float m_reg, l_reg = 0; bf16x8 qr[4]; f32x16 o[4];
; #pragma unroll
;   for (int d = 0; d < 4; ++d) o[d] = f32x16{};
;   const bf16* Qw = Qb + (long)(wid * 32 + r32) * LDK + hi * 8;
; #pragma unroll
;   for (int d0 = 0; d0 < 4; ++d0) qr[d0] = *(const GAS bf16x8*)(Qw + d0 * 16);
;   { float qs = 0.f;
; #pragma unroll
;     for (int d0 = 0; d0 < 4; ++d0)
; #pragma unroll
;       for (int j = 0; j < 8; ++j) { const float v = bf2f((unsigned short)qr[d0][j]); qs = fmaf(v, v, qs); }
;     { auto rr = __builtin_amdgcn_permlane32_swap(__float_as_uint(qs), __float_as_uint(qs), false, false); qs = __uint_as_float(rr[0]) + __uint_as_float(rr[1]); }
;     ...
;   if (pass == 0) {
; #pragma unroll
;     for (int r4 = 0; r4 < 4; ++r4) { const f32x4 lv = *(const f32x4*)(li_e + 8 * r4 + 4 * hi);
;       const f32x4 rl = (f32x4){__builtin_amdgcn_rcpf(lv[0]), __builtin_amdgcn_rcpf(lv[1]), __builtin_amdgcn_rcpf(lv[2]), __builtin_amdgcn_rcpf(lv[3])};
; #pragma unroll
;       for (int d0 = 0; d0 < 4; ++d0) scr4[d0 * 4 + r4] = (f32x4){o[d0][4 * r4 + 0] * rl[0], o[d0][4 * r4 + 1] * rl[1], o[d0][4 * r4 + 2] * rl[2], o[d0][4 * r4 + 3] * rl[3]}; }
.LBB0_321:
	s_or_b64 exec, exec, s[0:1]
	s_waitcnt lgkmcnt(0)
	v_add_u32_e32 v74, v66, v200
	ds_read_b128 v[66:69], v74
	ds_read_b128 v[70:73], v74 offset:32
	v_ashrrev_i32_e32 v147, 31, v146
	v_lshlrev_b64 v[0:1], 8, v[146:147]
	v_lshl_add_u64 v[0:1], s[40:41], 0, v[0:1]
	s_waitcnt lgkmcnt(1)
	v_rcp_f32_e32 v66, v66
	v_rcp_f32_e32 v67, v67
	v_rcp_f32_e32 v68, v68
	v_rcp_f32_e32 v69, v69
	v_readlane_b32 s0, v254, 39
	v_pk_mul_f32 v[2:3], v[2:3], v[66:67]
	v_mov_b32_e32 v146, v232
	v_pk_mul_f32 v[4:5], v[4:5], v[68:69]
	global_store_dwordx4 v[0:1], v[2:5], off
	v_mov_b32_e32 v201, v144
	s_nop 0
	v_pk_mul_f32 v[2:3], v[18:19], v[66:67]
	v_pk_mul_f32 v[4:5], v[20:21], v[68:69]
	s_waitcnt lgkmcnt(0)
	v_rcp_f32_e32 v18, v70
	v_rcp_f32_e32 v19, v71
	v_rcp_f32_e32 v20, v72
	v_rcp_f32_e32 v21, v73
	global_store_dwordx4 v[0:1], v[2:5], off offset:64
	s_nop 1
	v_pk_mul_f32 v[2:3], v[34:35], v[66:67]
	v_pk_mul_f32 v[4:5], v[36:37], v[68:69]
	global_store_dwordx4 v[0:1], v[2:5], off offset:128
	s_nop 1
	v_pk_mul_f32 v[2:3], v[50:51], v[66:67]
	v_pk_mul_f32 v[4:5], v[52:53], v[68:69]
	global_store_dwordx4 v[0:1], v[2:5], off offset:192
	s_nop 1
	v_pk_mul_f32 v[2:3], v[6:7], v[18:19]
	v_pk_mul_f32 v[4:5], v[8:9], v[20:21]
	global_store_dwordx4 v[0:1], v[2:5], off offset:16
	s_nop 1
	v_pk_mul_f32 v[2:3], v[22:23], v[18:19]
	v_pk_mul_f32 v[4:5], v[24:25], v[20:21]
	global_store_dwordx4 v[0:1], v[2:5], off offset:80
	s_nop 1
	v_pk_mul_f32 v[2:3], v[38:39], v[18:19]
	v_pk_mul_f32 v[4:5], v[40:41], v[20:21]
	global_store_dwordx4 v[0:1], v[2:5], off offset:144
	s_nop 1
	v_pk_mul_f32 v[2:3], v[54:55], v[18:19]
	v_pk_mul_f32 v[4:5], v[56:57], v[20:21]
	global_store_dwordx4 v[0:1], v[2:5], off offset:208
	ds_read_b128 v[2:5], v74 offset:64
	s_waitcnt lgkmcnt(0)
	v_rcp_f32_e32 v6, v2
	v_rcp_f32_e32 v7, v3
	v_rcp_f32_e32 v8, v4
	v_rcp_f32_e32 v9, v5
	v_pk_mul_f32 v[2:3], v[10:11], v[6:7]
	v_mov_b32_e32 v11, v144
	v_pk_mul_f32 v[4:5], v[12:13], v[8:9]
	global_store_dwordx4 v[0:1], v[2:5], off offset:32
	s_nop 1
	v_pk_mul_f32 v[2:3], v[26:27], v[6:7]
	v_pk_mul_f32 v[4:5], v[28:29], v[8:9]
	global_store_dwordx4 v[0:1], v[2:5], off offset:96
	s_nop 1
	v_pk_mul_f32 v[2:3], v[42:43], v[6:7]
	v_pk_mul_f32 v[4:5], v[44:45], v[8:9]
	global_store_dwordx4 v[0:1], v[2:5], off offset:160
	s_nop 1
	v_pk_mul_f32 v[2:3], v[58:59], v[6:7]
	v_pk_mul_f32 v[4:5], v[60:61], v[8:9]
	global_store_dwordx4 v[0:1], v[2:5], off offset:224
	ds_read_b128 v[2:5], v74 offset:96
	s_waitcnt lgkmcnt(0)
	v_rcp_f32_e32 v6, v2
	v_rcp_f32_e32 v7, v3
	v_rcp_f32_e32 v8, v4
	v_rcp_f32_e32 v9, v5
	v_pk_mul_f32 v[2:3], v[14:15], v[6:7]
	v_pk_mul_f32 v[4:5], v[16:17], v[8:9]
	global_store_dwordx4 v[0:1], v[2:5], off offset:48
	s_nop 1
	v_pk_mul_f32 v[2:3], v[30:31], v[6:7]
	v_pk_mul_f32 v[4:5], v[32:33], v[8:9]
	global_store_dwordx4 v[0:1], v[2:5], off offset:112
	s_nop 1
	v_pk_mul_f32 v[2:3], v[46:47], v[6:7]
	v_pk_mul_f32 v[4:5], v[48:49], v[8:9]
	global_store_dwordx4 v[0:1], v[2:5], off offset:176
	s_nop 1
	v_pk_mul_f32 v[2:3], v[62:63], v[6:7]
	v_pk_mul_f32 v[4:5], v[64:65], v[8:9]
	global_store_dwordx4 v[0:1], v[2:5], off offset:240
	v_mov_b32_e32 v0, s0
	ds_read_b32 v0, v0
	v_readlane_b32 s0, v254, 40
	v_bfe_u32 v217, v146, 5, 1
	v_lshlrev_b32_e32 v200, 4, v217
	v_lshlrev_b32_e32 v12, 3, v146
	s_waitcnt lgkmcnt(0)
	v_readfirstlane_b32 s62, v0
	v_mov_b32_e32 v0, s0
	ds_read_b32 v0, v0
	s_movk_i32 s0, 0xffe0
	v_bfe_u32 v5, v12, 5, 2
	v_lshlrev_b32_e32 v6, 4, v146
	v_and_b32_e32 v7, 48, v6
	s_waitcnt lgkmcnt(0)
	v_readfirstlane_b32 s63, v0
	v_ashrrev_i32_e32 v0, 1, v146
	v_and_b32_e32 v215, 0xffffffe0, v0
	v_add_u32_e32 v1, s39, v215
	v_bfi_b32 v0, s0, v0, v146
	v_readfirstlane_b32 s64, v1
	v_ashrrev_i32_e32 v1, 31, v0
	v_lshlrev_b64 v[0:1], 13, v[0:1]
	v_lshl_add_u64 v[0:1], s[52:53], 0, v[0:1]
	v_lshl_add_u64 v[0:1], v[0:1], 0, v[200:201]
	global_load_dwordx4 v[164:167], v[0:1], off offset:128
	global_load_dwordx4 v[160:163], v[0:1], off offset:160
	global_load_dwordx4 v[152:155], v[0:1], off offset:192
	global_load_dwordx4 v[156:159], v[0:1], off offset:224
	v_and_b32_e32 v10, 0x70, v6
	s_barrier
	v_and_b32_e32 v218, 31, v146
	v_add_u32_e32 v147, s64, v218
	s_waitcnt vmcnt(3)
	v_lshlrev_b32_e32 v0, 16, v164
	v_fma_f32 v0, v0, v0, 0
	v_and_b32_e32 v1, 0xffff0000, v164
	v_fmac_f32_e32 v0, v1, v1
	v_lshlrev_b32_e32 v1, 16, v165
	v_fmac_f32_e32 v0, v1, v1
	v_and_b32_e32 v1, 0xffff0000, v165
	v_fmac_f32_e32 v0, v1, v1
	v_lshlrev_b32_e32 v1, 16, v166
	v_fmac_f32_e32 v0, v1, v1
	v_and_b32_e32 v1, 0xffff0000, v166
	v_fmac_f32_e32 v0, v1, v1
	v_lshlrev_b32_e32 v1, 16, v167
	v_fmac_f32_e32 v0, v1, v1
	v_and_b32_e32 v1, 0xffff0000, v167
	v_fmac_f32_e32 v0, v1, v1
	s_waitcnt vmcnt(2)
	v_lshlrev_b32_e32 v1, 16, v160
	v_fmac_f32_e32 v0, v1, v1
	v_and_b32_e32 v1, 0xffff0000, v160
	v_fmac_f32_e32 v0, v1, v1
	v_lshlrev_b32_e32 v1, 16, v161
	v_fmac_f32_e32 v0, v1, v1
	v_and_b32_e32 v1, 0xffff0000, v161
	v_fmac_f32_e32 v0, v1, v1
	v_lshlrev_b32_e32 v1, 16, v162
	v_fmac_f32_e32 v0, v1, v1
	v_and_b32_e32 v1, 0xffff0000, v162
	v_fmac_f32_e32 v0, v1, v1
	v_lshlrev_b32_e32 v1, 16, v163
	v_fmac_f32_e32 v0, v1, v1
	v_and_b32_e32 v1, 0xffff0000, v163
	v_fmac_f32_e32 v0, v1, v1
	s_waitcnt vmcnt(1)
	v_lshlrev_b32_e32 v1, 16, v152
	v_fmac_f32_e32 v0, v1, v1
	v_and_b32_e32 v1, 0xffff0000, v152
	v_fmac_f32_e32 v0, v1, v1
	v_lshlrev_b32_e32 v1, 16, v153
	v_fmac_f32_e32 v0, v1, v1
	v_and_b32_e32 v1, 0xffff0000, v153
	v_fmac_f32_e32 v0, v1, v1
	v_lshlrev_b32_e32 v1, 16, v154
	v_fmac_f32_e32 v0, v1, v1
	v_and_b32_e32 v1, 0xffff0000, v154
	v_fmac_f32_e32 v0, v1, v1
	v_lshlrev_b32_e32 v1, 16, v155
	v_fmac_f32_e32 v0, v1, v1
	v_and_b32_e32 v1, 0xffff0000, v155
	v_fmac_f32_e32 v0, v1, v1
	s_waitcnt vmcnt(0)
; __device__ __forceinline__ int v_st(int k, int c) { const int kk = (k & ~0xC) | ((k & 4) << 1) | ((k & 8) >> 1); return ((kk >> 3) * 4 + (c >> 5)) * 512 + ((kk & 7) * 32 + (c & 31)) * 2; }
; __device__ __forceinline__ int v_rd_base(int lane) { return ((lane & 3) << 3) | (((lane >> 2) & 3) << 6) | (((lane >> 4) & 1) << 5) | (((lane >> 5) & 1) << 8); }
; #define SLOAD(i, k0) do { sr_[i].vs0 = *(const GAS bf16x8*)(&Vh[(long)((k0) + sr) * LDK + sc]); sr_[i].vs1 = *(const GAS bf16x8*)(&Vh[(long)((k0) + 32 + sr) * LDK + sc]); \
;     sr_[i].ks0 = *(const GAS bf16x8*)(&Kh[(long)((k0) + kr) * LDK + kc]); } while (0)
; #define SWRITE(b, i) do { *(bf16x8*)(V_lds + (b) * SHM_V + vst0) = sr_[i].vs0; *(bf16x8*)(V_lds + (b) * SHM_V + vst1) = sr_[i].vs1; \
;     *(bf16x8*)(K_lds + (b) * SHM_K + kst) = sr_[i].ks0; } while (0)
; template <bool GRPB> __device__ __forceinline__ void attn_pass(const float mbK, const float bmax2, const int pass, float* __restrict__ scr, bf16* __restrict__ mixrow, const float lam, const float* __restrict__ gsub, const float one_m_li, ...
;     ...
;     { auto rr = __builtin_amdgcn_permlane32_swap(__float_as_uint(qs), __float_as_uint(qs), false, false); qs = __uint_as_float(rr[0]) + __uint_as_float(rr[1]); }
;     m_reg = __builtin_sqrtf(qs) * mbK + bmax2 + 0.25f; }
;   const int sr = tid >> 4, sc = (tid & 15) * 8, vst0 = v_st(sr, sc), vst1 = v_st(32 + sr, sc);
;   const int kr = tid >> 3, kc = (tid & 7) * 8, kst = KSWZ64(kr, kc * 2);
;   const int vb0 = (int)(uintptr_t)V_lds + v_rd_base(lane);
;   struct { bf16x8 vs0, vs1, ks0; } sr_[2];
;     ...
;   f32x16 pA0, pA1, pB0, pB1; float mnA, mnB, alA, alB; bf16x8 pa0, pa1, pa2, pa3; constexpr int NT = SEQ / KVBLK;
;   __syncthreads();
;   SLOAD(0, 0); SLOAD(1, KVBLK); asm volatile("s_waitcnt vmcnt(0)" ::: "memory"); SWRITE(0, 0); SWRITE(1, 1);
;   SLOAD(0, 2 * KVBLK); asm volatile("s_waitcnt vmcnt(0)" ::: "memory"); SWRITE(2, 0); __syncthreads();
	v_lshlrev_b32_e32 v1, 16, v156
	v_fmac_f32_e32 v0, v1, v1
	v_and_b32_e32 v1, 0xffff0000, v156
	v_fmac_f32_e32 v0, v1, v1
	v_lshlrev_b32_e32 v1, 16, v157
	v_fmac_f32_e32 v0, v1, v1
	v_and_b32_e32 v1, 0xffff0000, v157
	v_fmac_f32_e32 v0, v1, v1
	v_lshlrev_b32_e32 v1, 16, v158
	v_fmac_f32_e32 v0, v1, v1
	v_and_b32_e32 v1, 0xffff0000, v158
	v_fmac_f32_e32 v0, v1, v1
	v_lshlrev_b32_e32 v1, 16, v159
	v_fmac_f32_e32 v0, v1, v1
	v_and_b32_e32 v1, 0xffff0000, v159
	v_fmac_f32_e32 v0, v1, v1
	v_mov_b32_e32 v1, v0
	s_nop 1
	v_permlane32_swap_b32_e32 v0, v1
	v_add_f32_e32 v0, v0, v1
	v_cmp_gt_f32_e32 vcc, s10, v0
	v_mul_f32_e32 v1, 0x4f800000, v0
	s_nop 0
	v_cndmask_b32_e32 v0, v0, v1, vcc
	v_sqrt_f32_e32 v1, v0
	s_nop 0
	v_add_u32_e32 v2, -1, v1
	v_fma_f32 v3, -v2, v1, v0
	v_cmp_ge_f32_e64 s[0:1], 0, v3
	v_add_u32_e32 v3, 1, v1
	s_nop 0
	v_cndmask_b32_e64 v2, v1, v2, s[0:1]
	v_fma_f32 v1, -v3, v1, v0
	v_cmp_lt_f32_e64 s[0:1], 0, v1
	s_nop 1
	v_cndmask_b32_e64 v1, v2, v3, s[0:1]
	v_mul_f32_e32 v2, 0x37800000, v1
	v_cndmask_b32_e32 v1, v1, v2, vcc
	v_cmp_class_f32_e32 vcc, v0, v198
	v_and_b32_e32 v2, 0x78, v12
	v_lshlrev_b32_e32 v6, 1, v2
	v_cndmask_b32_e32 v0, v1, v0, vcc
	v_fma_f32 v0, v214, v0, s45
	v_add_f32_e32 v64, 0x3e800000, v0
	v_ashrrev_i32_e32 v0, 4, v146
	v_and_b32_e32 v1, 0xfffff0, v0
	v_lshlrev_b32_e32 v3, 1, v0
	v_and_or_b32 v1, v3, 8, v1
	v_lshrrev_b32_e32 v3, 1, v0
	v_lshrrev_b32_e32 v1, 1, v1
	v_and_b32_e32 v4, 3, v0
	v_or_b32_e32 v1, v1, v5
	v_and_or_b32 v3, v3, 4, v4
	v_lshlrev_b32_e32 v1, 9, v1
	v_lshlrev_b32_e32 v3, 6, v3
	v_add_u32_e32 v4, 32, v0
	v_or3_b32 v221, v1, v3, v7
	v_and_b32_e32 v1, 0xfffff0, v4
	v_lshlrev_b32_e32 v8, 1, v4
	v_and_or_b32 v1, v8, 8, v1
	v_lshrrev_b32_e32 v1, 1, v1
	v_or_b32_e32 v1, v1, v5
	v_lshlrev_b32_e32 v1, 9, v1
	v_ashrrev_i32_e32 v8, 3, v146
	v_or3_b32 v222, v1, v3, v7
	v_lshlrev_b32_e32 v1, 7, v8
	v_and_b32_e32 v3, 0x70, v146
	v_bitop3_b32 v223, v10, v1, v3 bitop3:0xde
	v_ashrrev_i32_e32 v1, 31, v0
	v_lshlrev_b64 v[48:49], 13, v[0:1]
	v_lshl_add_u64 v[0:1], s[50:51], 0, v[48:49]
	v_mov_b32_e32 v7, v144
	v_ashrrev_i32_e32 v5, 31, v4
	v_lshl_add_u64 v[26:27], v[0:1], 0, v[6:7]
	v_lshlrev_b64 v[4:5], 13, v[4:5]
	global_load_dwordx4 v[0:3], v[26:27], off offset:2048
	v_lshl_add_u64 v[4:5], s[50:51], 0, v[4:5]
	v_ashrrev_i32_e32 v9, 31, v8
	s_mov_b32 s0, 0x80000
	v_lshl_add_u64 v[4:5], v[4:5], 0, v[6:7]
	v_lshlrev_b64 v[50:51], 13, v[8:9]
	v_add_co_u32_e32 v14, vcc, s0, v26
	global_load_dwordx4 v[4:7], v[4:5], off offset:2048
	v_lshl_add_u64 v[8:9], s[50:51], 0, v[50:51]
	v_addc_co_u32_e32 v15, vcc, 0, v27, vcc
	s_mov_b32 s1, 0xc0000
	v_lshl_add_u64 v[28:29], v[8:9], 0, v[10:11]
	v_add_co_u32_e32 v18, vcc, s1, v26
	global_load_dwordx4 v[8:11], v[28:29], off offset:1152
	s_nop 0
	v_addc_co_u32_e32 v19, vcc, 0, v27, vcc
	global_load_dwordx4 v[14:17], v[14:15], off offset:2048
	v_add_co_u32_e32 v22, vcc, s0, v28
	global_load_dwordx4 v[18:21], v[18:19], off offset:2048
	s_nop 0
	v_addc_co_u32_e32 v23, vcc, 0, v29, vcc
	global_load_dwordx4 v[22:25], v[22:23], off offset:1152
	v_add_u32_e32 v13, 0, v221
	s_mov_b32 s0, 0x100000
	s_waitcnt vmcnt(3)
	v_add_u32_e32 v30, 0, v222
	s_mov_b32 s1, 0x140000
	v_add_u32_e32 v224, 0, v223
	s_waitcnt vmcnt(5)
	ds_write_b128 v13, v[0:3]
	v_add_co_u32_e32 v0, vcc, s0, v26
	s_waitcnt vmcnt(4)
	ds_write_b128 v30, v[4:7]
	v_addc_co_u32_e32 v1, vcc, 0, v27, vcc
	v_add_co_u32_e32 v4, vcc, s1, v26
	s_waitcnt vmcnt(3)
	ds_write_b128 v224, v[8:11] offset:49152
	v_addc_co_u32_e32 v5, vcc, 0, v27, vcc
	v_add_co_u32_e32 v8, vcc, s0, v28
	global_load_dwordx4 v[0:3], v[0:1], off offset:2048
	s_nop 0
	v_addc_co_u32_e32 v9, vcc, 0, v29, vcc
	global_load_dwordx4 v[4:7], v[4:5], off offset:2048
	s_nop 0
	global_load_dwordx4 v[8:11], v[8:9], off offset:1152
	s_waitcnt vmcnt(5)
	ds_write_b128 v13, v[14:17] offset:16384
	s_waitcnt vmcnt(4)
	ds_write_b128 v30, v[18:21] offset:16384
	s_waitcnt vmcnt(3)
	ds_write_b128 v224, v[22:25] offset:57344
	s_waitcnt vmcnt(2)
	ds_write_b128 v13, v[0:3] offset:32768
	s_waitcnt vmcnt(1)
	ds_write_b128 v30, v[4:7] offset:32768
	v_add_u32_e32 v0, 0x10000, v224
	s_waitcnt vmcnt(0)
	ds_write_b128 v0, v[8:11]
	v_lshlrev_b32_e32 v8, 7, v218
	v_and_b32_e32 v9, 0x70, v12
	v_or_b32_e32 v10, 32, v200
	v_bitop3_b32 v229, v10, v8, v9 bitop3:0xde
	v_or_b32_e32 v10, 64, v200
	v_bitop3_b32 v231, v10, v8, v9 bitop3:0xde
	v_or_b32_e32 v10, 0x60, v200
	v_bitop3_b32 v226, v200, v8, v9 bitop3:0xde
	v_bitop3_b32 v240, v10, v8, v9 bitop3:0xde
	v_add_u32_e32 v225, 0, v226
	v_add_u32_e32 v227, 0, v229
	v_add_u32_e32 v228, 0, v231
	v_add_u32_e32 v230, 0, v240
	s_waitcnt lgkmcnt(0)
	s_barrier
; #define SBAR() __builtin_amdgcn_sched_barrier(0)
; __device__ __forceinline__ void partialSM(f32x16& p0, f32x16& p1, float& m_reg, float& mn, float& alpha, int kt0, int qpos, int qw, int hi, const float* tb2, float cL, float cR) {
;   mn = m_reg; alpha = 1.f;
;   const int rel_hi = kt0 + 63 - qw, rel_lo = kt0 - (qw + 31);
;   if (rel_hi <= -91 || rel_lo >= 91) {
;     const float cm = ((rel_hi <= -91) ? cL : cR) - m_reg;
; #pragma unroll
;     for (int r = 0; r < 16; ++r) { p0[r] = fmaf(p0[r], C1, cm); p1[r] = fmaf(p1[r], C1, cm); }
;   } else {
;     const float* tp = tb2 + (kt0 - qpos + 192 + 4 * hi);
; #pragma unroll
;     for (int r4 = 0; r4 < 4; ++r4) {
;       float ta[4], tb[4];
; #pragma unroll
;       for (int i = 0; i < 4; ++i) { ta[i] = tp[8 * r4 + i] - m_reg; tb[i] = tp[32 + 8 * r4 + i] - m_reg; }
; #pragma unroll
;       for (int i = 0; i < 4; ++i) { p0[4 * r4 + i] = fmaf(p0[4 * r4 + i], C1, ta[i]); p1[4 * r4 + i] = fmaf(p1[4 * r4 + i], C1, tb[i]); }
;       asm volatile("" ::: "memory");
;     }
; __device__ __forceinline__ void qkt(f32x16& p0, f32x16& p1, const char* Ks, const bf16x8* qr, int r32, int hi) {
;   bf16x8 ka[4], kb[4];
; #pragma unroll
;   for (int d0 = 0; d0 < 4; ++d0) { const int cb = (d0 * 16 + hi * 8) * 2;
;     ka[d0] = *reinterpret_cast<const bf16x8*>(Ks + KSWZ64(r32, cb)); kb[d0] = *reinterpret_cast<const bf16x8*>(Ks + KSWZ64(32 + r32, cb)); }
;   asm volatile("s_waitcnt lgkmcnt(0)" ::: "memory"); SBAR();
;   p0 = f32x16{}; p1 = f32x16{};
; #pragma unroll
;   for (int d0 = 0; d0 < 4; ++d0) {
;     p0 = __builtin_amdgcn_mfma_f32_32x32x16_bf16(ka[d0], qr[d0], p0, 0, 0, 0);
;     p1 = __builtin_amdgcn_mfma_f32_32x32x16_bf16(kb[d0], qr[d0], p1, 0, 0, 0); }
	ds_read_b128 v[0:3], v225 offset:49152
	ds_read_b128 v[4:7], v225 offset:53248
	ds_read_b128 v[32:35], v227 offset:49152
	ds_read_b128 v[36:39], v227 offset:53248
	ds_read_b128 v[40:43], v228 offset:49152
	ds_read_b128 v[44:47], v228 offset:53248
	ds_read_b128 v[52:55], v230 offset:49152
	ds_read_b128 v[56:59], v230 offset:53248
	s_waitcnt lgkmcnt(0)
	s_waitcnt lgkmcnt(7)
	v_mfma_f32_32x32x16_bf16 v[16:31], v[0:3], v[164:167], 0
	s_add_i32 s4, s64, 0xffffff66
	s_mov_b64 s[0:1], -1
	s_cmp_gt_u32 s4, 0xfffffeec
	s_waitcnt lgkmcnt(6)
	v_mfma_f32_32x32x16_bf16 v[0:15], v[4:7], v[164:167], 0
	s_waitcnt lgkmcnt(5)
	v_mfma_f32_32x32x16_bf16 v[16:31], v[32:35], v[160:163], v[16:31]
	s_waitcnt lgkmcnt(4)
	v_mfma_f32_32x32x16_bf16 v[0:15], v[36:39], v[160:163], v[0:15]
	s_waitcnt lgkmcnt(3)
	v_mfma_f32_32x32x16_bf16 v[16:31], v[40:43], v[152:155], v[16:31]
	s_waitcnt lgkmcnt(2)
	v_mfma_f32_32x32x16_bf16 v[0:15], v[44:47], v[152:155], v[0:15]
	s_waitcnt lgkmcnt(1)
	v_mfma_f32_32x32x16_bf16 v[16:31], v[52:55], v[156:159], v[16:31]
	v_lshlrev_b32_e32 v52, 2, v147
	s_waitcnt lgkmcnt(0)
	v_mfma_f32_32x32x16_bf16 v[0:15], v[56:59], v[156:159], v[0:15]
	s_cbranch_scc0 .LBB0_323
	v_sub_u32_e32 v32, 0, v52
	s_mov_b32 s0, 0x12b00
	v_add3_u32 v53, v32, v200, s0
	ds_read2_b32 v[32:33], v53 offset1:1
	ds_read2_b32 v[54:55], v53 offset0:32 offset1:33
	ds_read2_b32 v[56:57], v53 offset0:34 offset1:35
	ds_read2_b32 v[34:35], v53 offset0:2 offset1:3
	ds_read2_b32 v[36:37], v53 offset0:8 offset1:9
	ds_read2_b32 v[58:59], v53 offset0:40 offset1:41
	ds_read2_b32 v[60:61], v53 offset0:42 offset1:43
	ds_read2_b32 v[38:39], v53 offset0:10 offset1:11
	ds_read2_b32 v[40:41], v53 offset0:16 offset1:17
	ds_read2_b32 v[62:63], v53 offset0:48 offset1:49
	ds_read2_b32 v[66:67], v53 offset0:50 offset1:51
	ds_read2_b32 v[42:43], v53 offset0:18 offset1:19
	ds_read2_b32 v[44:45], v53 offset0:24 offset1:25
	ds_read2_b32 v[46:47], v53 offset0:26 offset1:27
	ds_read2_b32 v[68:69], v53 offset0:58 offset1:59
	ds_read2_b32 v[70:71], v53 offset0:56 offset1:57
	s_waitcnt lgkmcnt(3)
	v_sub_f32_e32 v45, v45, v64
	v_sub_f32_e32 v44, v44, v64
	s_waitcnt lgkmcnt(2)
	v_sub_f32_e32 v47, v47, v64
	v_sub_f32_e32 v46, v46, v64
	v_sub_f32_e32 v41, v41, v64
	v_sub_f32_e32 v40, v40, v64
	v_sub_f32_e32 v43, v43, v64
	v_sub_f32_e32 v42, v42, v64
	v_sub_f32_e32 v37, v37, v64
	v_sub_f32_e32 v36, v36, v64
	v_sub_f32_e32 v39, v39, v64
	v_sub_f32_e32 v38, v38, v64
	v_sub_f32_e32 v33, v33, v64
	v_sub_f32_e32 v32, v32, v64
	v_sub_f32_e32 v35, v35, v64
	v_sub_f32_e32 v34, v34, v64
	s_waitcnt lgkmcnt(0)
	v_sub_f32_e32 v71, v71, v64
	v_sub_f32_e32 v70, v70, v64
	v_sub_f32_e32 v69, v69, v64
	v_sub_f32_e32 v68, v68, v64
	v_sub_f32_e32 v63, v63, v64
	v_sub_f32_e32 v62, v62, v64
	v_sub_f32_e32 v67, v67, v64
	v_sub_f32_e32 v66, v66, v64
	v_sub_f32_e32 v59, v59, v64
	v_sub_f32_e32 v58, v58, v64
	v_sub_f32_e32 v61, v61, v64
	v_sub_f32_e32 v60, v60, v64
	v_sub_f32_e32 v55, v55, v64
	v_sub_f32_e32 v54, v54, v64
	v_sub_f32_e32 v57, v57, v64
	v_sub_f32_e32 v56, v56, v64
	v_pk_fma_f32 v[34:35], v[18:19], s[6:7], v[34:35] op_sel_hi:[1,0,1]
	v_pk_fma_f32 v[32:33], v[16:17], s[6:7], v[32:33] op_sel_hi:[1,0,1]
	v_pk_fma_f32 v[38:39], v[22:23], s[6:7], v[38:39] op_sel_hi:[1,0,1]
	v_pk_fma_f32 v[36:37], v[20:21], s[6:7], v[36:37] op_sel_hi:[1,0,1]
	v_pk_fma_f32 v[42:43], v[26:27], s[6:7], v[42:43] op_sel_hi:[1,0,1]
	v_pk_fma_f32 v[40:41], v[24:25], s[6:7], v[40:41] op_sel_hi:[1,0,1]
	v_pk_fma_f32 v[46:47], v[30:31], s[6:7], v[46:47] op_sel_hi:[1,0,1]
	v_pk_fma_f32 v[44:45], v[28:29], s[6:7], v[44:45] op_sel_hi:[1,0,1]
	v_pk_fma_f32 v[82:83], v[2:3], s[6:7], v[56:57] op_sel_hi:[1,0,1]
	v_pk_fma_f32 v[80:81], v[0:1], s[6:7], v[54:55] op_sel_hi:[1,0,1]
	v_pk_fma_f32 v[86:87], v[6:7], s[6:7], v[60:61] op_sel_hi:[1,0,1]
	v_pk_fma_f32 v[84:85], v[4:5], s[6:7], v[58:59] op_sel_hi:[1,0,1]
	v_pk_fma_f32 v[90:91], v[10:11], s[6:7], v[66:67] op_sel_hi:[1,0,1]
	v_pk_fma_f32 v[88:89], v[8:9], s[6:7], v[62:63] op_sel_hi:[1,0,1]
	v_pk_fma_f32 v[94:95], v[14:15], s[6:7], v[68:69] op_sel_hi:[1,0,1]
	v_pk_fma_f32 v[92:93], v[12:13], s[6:7], v[70:71] op_sel_hi:[1,0,1]
	s_mov_b64 s[0:1], 0

; #define GAS __attribute__((address_space(1)))
; __device__ __forceinline__ float bf2f(unsigned short b) { return __uint_as_float(((unsigned)b) << 16); }
; __device__ __forceinline__ int v_st(int k, int c) { const int kk = (k & ~0xC) | ((k & 4) << 1) | ((k & 8) >> 1); return ((kk >> 3) * 4 + (c >> 5)) * 512 + ((kk & 7) * 32 + (c & 31)) * 2; }
; __device__ __forceinline__ int v_rd_base(int lane) { return ((lane & 3) << 3) | (((lane >> 2) & 3) << 6) | (((lane >> 4) & 1) << 5) | (((lane >> 5) & 1) << 8); }
; template <bool GRPB> __device__ __forceinline__ void attn_pass(const float mbK, const float bmax2, const int pass, float* __restrict__ scr, bf16* __restrict__ mixrow, const float lam, const float* __restrict__ gsub, const float one_m_li, ...
;     ...
;   const float cL = __uint_as_float(__builtin_amdgcn_readfirstlane(__float_as_uint(tb2[0]))), cR = __uint_as_float(__builtin_amdgcn_readfirstlane(__float_as_uint(tb2[384])));
;   const int qw = __builtin_amdgcn_readfirstlane(q0seq + wid * 32), qpos = qw + r32;
;   float m_reg, l_reg = 0; bf16x8 qr[4]; f32x16 o[4];
; #pragma unroll
;   for (int d = 0; d < 4; ++d) o[d] = f32x16{};
;   const bf16* Qw = Qb + (long)(wid * 32 + r32) * LDK + hi * 8;
; #pragma unroll
;   for (int d0 = 0; d0 < 4; ++d0) qr[d0] = *(const GAS bf16x8*)(Qw + d0 * 16);
;   { float qs = 0.f;
; #pragma unroll
;     for (int d0 = 0; d0 < 4; ++d0)
; #pragma unroll
;       for (int j = 0; j < 8; ++j) { const float v = bf2f((unsigned short)qr[d0][j]); qs = fmaf(v, v, qs); }
;     { auto rr = __builtin_amdgcn_permlane32_swap(__float_as_uint(qs), __float_as_uint(qs), false, false); qs = __uint_as_float(rr[0]) + __uint_as_float(rr[1]); }
;     m_reg = __builtin_sqrtf(qs) * mbK + bmax2 + 0.25f; }
;   const int sr = tid >> 4, sc = (tid & 15) * 8, vst0 = v_st(sr, sc), vst1 = v_st(32 + sr, sc);
;   const int kr = tid >> 3, kc = (tid & 7) * 8, kst = KSWZ64(kr, kc * 2);
;   const int vb0 = (int)(uintptr_t)V_lds + v_rd_base(lane);
;   struct { bf16x8 vs0, vs1, ks0; } sr_[2];
;     ...
;   f32x16 pA0, pA1, pB0, pB1; float mnA, mnB, alA, alB; bf16x8 pa0, pa1, pa2, pa3; constexpr int NT = SEQ / KVBLK;
;   __syncthreads();
;   SLOAD(0, 0); SLOAD(1, KVBLK); asm volatile("s_waitcnt vmcnt(0)" ::: "memory"); SWRITE(0, 0); SWRITE(1, 1);
.LBB0_347:
	s_and_b64 vcc, exec, s[0:1]
	s_cbranch_vccz .LBB0_249
	v_readlane_b32 s0, v254, 39
	v_mov_b32_e32 v146, v232
	v_mov_b32_e32 v181, v144
	v_mov_b32_e32 v0, s0
	ds_read_b32 v0, v0
	v_readlane_b32 s0, v254, 40
	v_lshrrev_b32_e32 v2, 1, v146
	v_and_b32_e32 v180, 16, v2
	v_lshlrev_b32_e32 v8, 4, v146
	s_waitcnt lgkmcnt(0)
	v_readfirstlane_b32 s54, v0
	v_mov_b32_e32 v0, s0
	ds_read_b32 v0, v0
	s_movk_i32 s0, 0xffe0
	v_and_b32_e32 v9, 48, v8
	v_ashrrev_i32_e32 v12, 3, v146
	v_ashrrev_i32_e32 v13, 31, v12
	s_waitcnt lgkmcnt(0)
	v_readfirstlane_b32 s55, v0
	v_ashrrev_i32_e32 v0, 1, v146
	v_and_b32_e32 v1, 0xffffffe0, v0
	v_add_u32_e32 v1, s39, v1
	v_bfi_b32 v0, s0, v0, v146
	v_readfirstlane_b32 s60, v1
	v_ashrrev_i32_e32 v1, 31, v0
	v_lshlrev_b64 v[0:1], 13, v[0:1]
	v_lshl_add_u64 v[0:1], s[52:53], 0, v[0:1]
	v_lshl_add_u64 v[0:1], v[0:1], 0, v[180:181]
	global_load_dwordx4 v[164:167], v[0:1], off
	global_load_dwordx4 v[160:163], v[0:1], off offset:32
	global_load_dwordx4 v[156:159], v[0:1], off offset:64
	global_load_dwordx4 v[152:155], v[0:1], off offset:96
	s_barrier
	v_lshlrev_b64 v[52:53], 13, v[12:13]
	v_mov_b32_e32 v11, v144
	v_and_b32_e32 v147, 31, v146
	v_add_u32_e32 v190, s60, v147
	s_waitcnt vmcnt(3)
	v_lshlrev_b32_e32 v0, 16, v164
	v_fma_f32 v0, v0, v0, 0
	v_and_b32_e32 v1, 0xffff0000, v164
	v_fmac_f32_e32 v0, v1, v1
	v_lshlrev_b32_e32 v1, 16, v165
	v_fmac_f32_e32 v0, v1, v1
	v_and_b32_e32 v1, 0xffff0000, v165
	v_fmac_f32_e32 v0, v1, v1
	v_lshlrev_b32_e32 v1, 16, v166
	v_fmac_f32_e32 v0, v1, v1
	v_and_b32_e32 v1, 0xffff0000, v166
	v_fmac_f32_e32 v0, v1, v1
	v_lshlrev_b32_e32 v1, 16, v167
	v_fmac_f32_e32 v0, v1, v1
	v_and_b32_e32 v1, 0xffff0000, v167
	v_fmac_f32_e32 v0, v1, v1
	s_waitcnt vmcnt(2)
	v_lshlrev_b32_e32 v1, 16, v160
	v_fmac_f32_e32 v0, v1, v1
	v_and_b32_e32 v1, 0xffff0000, v160
	v_fmac_f32_e32 v0, v1, v1
	v_lshlrev_b32_e32 v1, 16, v161
	v_fmac_f32_e32 v0, v1, v1
	v_and_b32_e32 v1, 0xffff0000, v161
	v_fmac_f32_e32 v0, v1, v1
	v_lshlrev_b32_e32 v1, 16, v162
	v_fmac_f32_e32 v0, v1, v1
	v_and_b32_e32 v1, 0xffff0000, v162
	v_fmac_f32_e32 v0, v1, v1
	v_lshlrev_b32_e32 v1, 16, v163
	v_fmac_f32_e32 v0, v1, v1
	v_and_b32_e32 v1, 0xffff0000, v163
	v_fmac_f32_e32 v0, v1, v1
	s_waitcnt vmcnt(1)
	v_lshlrev_b32_e32 v1, 16, v156
	v_fmac_f32_e32 v0, v1, v1
	v_and_b32_e32 v1, 0xffff0000, v156
	v_fmac_f32_e32 v0, v1, v1
	v_lshlrev_b32_e32 v1, 16, v157
	v_fmac_f32_e32 v0, v1, v1
	v_and_b32_e32 v1, 0xffff0000, v157
	v_fmac_f32_e32 v0, v1, v1
	v_lshlrev_b32_e32 v1, 16, v158
	v_fmac_f32_e32 v0, v1, v1
	v_and_b32_e32 v1, 0xffff0000, v158
	v_fmac_f32_e32 v0, v1, v1
	v_lshlrev_b32_e32 v1, 16, v159
	v_fmac_f32_e32 v0, v1, v1
	v_and_b32_e32 v1, 0xffff0000, v159
	v_fmac_f32_e32 v0, v1, v1
	s_waitcnt vmcnt(0)
	v_lshlrev_b32_e32 v1, 16, v152
	v_fmac_f32_e32 v0, v1, v1
	v_and_b32_e32 v1, 0xffff0000, v152
	v_fmac_f32_e32 v0, v1, v1
	v_lshlrev_b32_e32 v1, 16, v153
	v_fmac_f32_e32 v0, v1, v1
	v_and_b32_e32 v1, 0xffff0000, v153
	v_fmac_f32_e32 v0, v1, v1
	v_lshlrev_b32_e32 v1, 16, v154
	v_fmac_f32_e32 v0, v1, v1
	v_and_b32_e32 v1, 0xffff0000, v154
	v_fmac_f32_e32 v0, v1, v1
	v_lshlrev_b32_e32 v1, 16, v155
	v_fmac_f32_e32 v0, v1, v1
	v_and_b32_e32 v1, 0xffff0000, v155
	v_fmac_f32_e32 v0, v1, v1
	v_mov_b32_e32 v1, v0
	s_nop 1
	v_permlane32_swap_b32_e32 v0, v1
	v_add_f32_e32 v0, v0, v1
	v_cmp_gt_f32_e32 vcc, s10, v0
	v_mul_f32_e32 v1, 0x4f800000, v0
	s_nop 0
	v_cndmask_b32_e32 v0, v0, v1, vcc
	v_sqrt_f32_e32 v1, v0
	s_nop 0
	v_add_u32_e32 v2, -1, v1
	v_fma_f32 v3, -v2, v1, v0
	v_cmp_ge_f32_e64 s[0:1], 0, v3
	v_add_u32_e32 v3, 1, v1
	s_nop 0
	v_cndmask_b32_e64 v2, v1, v2, s[0:1]
	v_fma_f32 v1, -v3, v1, v0
	v_cmp_lt_f32_e64 s[0:1], 0, v1
	s_nop 1
	v_cndmask_b32_e64 v1, v2, v3, s[0:1]
	v_mul_f32_e32 v2, 0x37800000, v1
	v_cndmask_b32_e32 v1, v1, v2, vcc
	v_ashrrev_i32_e32 v2, 4, v146
	v_cmp_class_f32_e32 vcc, v0, v198
	v_and_b32_e32 v3, 0xfffff0, v2
	v_lshlrev_b32_e32 v5, 1, v2
	v_cndmask_b32_e32 v0, v1, v0, vcc
	v_lshlrev_b32_e32 v1, 3, v146
	v_and_or_b32 v3, v5, 8, v3
	v_lshrrev_b32_e32 v5, 1, v2
	v_lshrrev_b32_e32 v3, 1, v3
	v_bfe_u32 v7, v1, 5, 2
	v_and_b32_e32 v6, 3, v2
	v_or_b32_e32 v3, v3, v7
	v_and_or_b32 v5, v5, 4, v6
	v_lshlrev_b32_e32 v3, 9, v3
	v_lshlrev_b32_e32 v5, 6, v5
	v_add_u32_e32 v6, 32, v2
	v_or3_b32 v181, v3, v5, v9
	v_and_b32_e32 v3, 0xfffff0, v6
	v_lshlrev_b32_e32 v10, 1, v6
	v_and_or_b32 v3, v10, 8, v3
	v_lshrrev_b32_e32 v3, 1, v3
	v_or_b32_e32 v3, v3, v7
	v_lshlrev_b32_e32 v3, 9, v3
	v_or3_b32 v191, v3, v5, v9
	v_lshlrev_b32_e32 v3, 7, v12
	v_and_b32_e32 v10, 0x70, v8
	v_and_b32_e32 v5, 0x70, v146
	v_bitop3_b32 v192, v10, v3, v5 bitop3:0xde
	v_ashrrev_i32_e32 v3, 31, v2
	v_and_b32_e32 v4, 0x78, v1
	v_lshlrev_b64 v[50:51], 13, v[2:3]
	v_lshl_add_u64 v[2:3], s[50:51], 0, v[50:51]
	v_lshlrev_b32_e32 v8, 1, v4
	v_mov_b32_e32 v9, v144
	v_ashrrev_i32_e32 v7, 31, v6
	v_lshl_add_u64 v[18:19], v[2:3], 0, v[8:9]
	v_lshlrev_b64 v[6:7], 13, v[6:7]
	global_load_dwordx4 v[2:5], v[18:19], off offset:2048
	v_lshl_add_u64 v[6:7], s[50:51], 0, v[6:7]
	s_mov_b32 s0, 0x80000
	v_lshl_add_u64 v[6:7], v[6:7], 0, v[8:9]
	v_add_co_u32_e32 v14, vcc, s0, v18
	global_load_dwordx4 v[6:9], v[6:7], off offset:2048
	v_lshl_add_u64 v[12:13], s[50:51], 0, v[52:53]
	v_addc_co_u32_e32 v15, vcc, 0, v19, vcc
	s_mov_b32 s1, 0xc0000
	v_lshl_add_u64 v[20:21], v[12:13], 0, v[10:11]
	v_add_co_u32_e32 v22, vcc, s1, v18
	global_load_dwordx4 v[10:13], v[20:21], off offset:1024
	s_nop 0
	v_addc_co_u32_e32 v23, vcc, 0, v19, vcc
	global_load_dwordx4 v[14:17], v[14:15], off offset:2048
	v_add_co_u32_e32 v26, vcc, s0, v20
	global_load_dwordx4 v[22:25], v[22:23], off offset:2048
	s_nop 0
	v_addc_co_u32_e32 v27, vcc, 0, v21, vcc
	global_load_dwordx4 v[26:29], v[26:27], off offset:1024
	v_add_u32_e32 v30, 0, v181
	s_mov_b32 s0, 0x100000
	s_waitcnt vmcnt(3)
; #define SLOAD(i, k0) do { sr_[i].vs0 = *(const GAS bf16x8*)(&Vh[(long)((k0) + sr) * LDK + sc]); sr_[i].vs1 = *(const GAS bf16x8*)(&Vh[(long)((k0) + 32 + sr) * LDK + sc]); \
;     sr_[i].ks0 = *(const GAS bf16x8*)(&Kh[(long)((k0) + kr) * LDK + kc]); } while (0)
; #define SWRITE(b, i) do { *(bf16x8*)(V_lds + (b) * SHM_V + vst0) = sr_[i].vs0; *(bf16x8*)(V_lds + (b) * SHM_V + vst1) = sr_[i].vs1; \
;     *(bf16x8*)(K_lds + (b) * SHM_K + kst) = sr_[i].ks0; } while (0)
; __device__ __forceinline__ void partialSM(f32x16& p0, f32x16& p1, float& m_reg, float& mn, float& alpha, int kt0, int qpos, int qw, int hi, const float* tb2, float cL, float cR) {
;   mn = m_reg; alpha = 1.f;
;   const int rel_hi = kt0 + 63 - qw, rel_lo = kt0 - (qw + 31);
;   if (rel_hi <= -91 || rel_lo >= 91) {
;     const float cm = ((rel_hi <= -91) ? cL : cR) - m_reg;
; #pragma unroll
;     for (int r = 0; r < 16; ++r) { p0[r] = fmaf(p0[r], C1, cm); p1[r] = fmaf(p1[r], C1, cm); }
;   } else {
;     const float* tp = tb2 + (kt0 - qpos + 192 + 4 * hi);
; #pragma unroll
;     for (int r4 = 0; r4 < 4; ++r4) {
;       float ta[4], tb[4];
; #pragma unroll
;       for (int i = 0; i < 4; ++i) { ta[i] = tp[8 * r4 + i] - m_reg; tb[i] = tp[32 + 8 * r4 + i] - m_reg; }
; #pragma unroll
;       for (int i = 0; i < 4; ++i) { p0[4 * r4 + i] = fmaf(p0[4 * r4 + i], C1, ta[i]); p1[4 * r4 + i] = fmaf(p1[4 * r4 + i], C1, tb[i]); }
;       asm volatile("" ::: "memory");
;     }
; template <bool GRPB> __device__ __forceinline__ void attn_pass(const float mbK, const float bmax2, const int pass, float* __restrict__ scr, bf16* __restrict__ mixrow, const float lam, const float* __restrict__ gsub, const float one_m_li, ...
;     ...
;   SLOAD(0, 0); SLOAD(1, KVBLK); asm volatile("s_waitcnt vmcnt(0)" ::: "memory"); SWRITE(0, 0); SWRITE(1, 1);
;   SLOAD(0, 2 * KVBLK); asm volatile("s_waitcnt vmcnt(0)" ::: "memory"); SWRITE(2, 0); __syncthreads();
;   qkt(pA0, pA1, K_lds, qr, r32, hi); partialSM(pA0, pA1, m_reg, mnA, alA, 0, qpos, qw, hi, tb2, cL, cR);
	v_add_u32_e32 v31, 0, v191
	s_mov_b32 s1, 0x140000
	v_add_u32_e32 v200, 0, v192
	v_and_b32_e32 v1, 0x70, v1
	v_fma_f32 v0, v216, v0, s45
	v_add_f32_e32 v0, 0x3e800000, v0
	s_waitcnt vmcnt(5)
	ds_write_b128 v30, v[2:5]
	v_add_co_u32_e32 v2, vcc, s0, v18
	s_waitcnt vmcnt(4)
	ds_write_b128 v31, v[6:9]
	v_addc_co_u32_e32 v3, vcc, 0, v19, vcc
	v_add_co_u32_e32 v6, vcc, s1, v18
	s_waitcnt vmcnt(3)
	ds_write_b128 v200, v[10:13] offset:49152
	v_addc_co_u32_e32 v7, vcc, 0, v19, vcc
	v_add_co_u32_e32 v10, vcc, s0, v20
	global_load_dwordx4 v[2:5], v[2:3], off offset:2048
	s_nop 0
	v_addc_co_u32_e32 v11, vcc, 0, v21, vcc
	global_load_dwordx4 v[6:9], v[6:7], off offset:2048
	s_nop 0
	global_load_dwordx4 v[10:13], v[10:11], off offset:1024
	s_waitcnt vmcnt(5)
	ds_write_b128 v30, v[14:17] offset:16384
	s_waitcnt vmcnt(4)
	ds_write_b128 v31, v[22:25] offset:16384
	s_waitcnt vmcnt(3)
	ds_write_b128 v200, v[26:29] offset:57344
	s_waitcnt vmcnt(2)
	ds_write_b128 v30, v[2:5] offset:32768
	s_waitcnt vmcnt(1)
	ds_write_b128 v31, v[6:9] offset:32768
	v_add_u32_e32 v2, 0x10000, v200
	s_waitcnt vmcnt(0)
	ds_write_b128 v2, v[10:13]
	v_lshlrev_b32_e32 v10, 7, v147
	v_or_b32_e32 v11, 32, v180
	v_bitop3_b32 v205, v11, v10, v1 bitop3:0xde
	v_or_b32_e32 v11, 64, v180
	v_bitop3_b32 v207, v11, v10, v1 bitop3:0xde
	v_or_b32_e32 v11, 0x60, v180
	v_bitop3_b32 v202, v180, v10, v1 bitop3:0xde
	v_bitop3_b32 v208, v11, v10, v1 bitop3:0xde
	v_add_u32_e32 v201, 0, v202
	v_add_u32_e32 v203, 0, v205
	v_add_u32_e32 v204, 0, v207
	v_add_u32_e32 v206, 0, v208
	s_waitcnt lgkmcnt(0)
	s_barrier
	ds_read_b128 v[2:5], v201 offset:49152
	ds_read_b128 v[6:9], v201 offset:53248
	ds_read_b128 v[34:37], v203 offset:49152
	ds_read_b128 v[38:41], v203 offset:53248
	ds_read_b128 v[42:45], v204 offset:49152
	ds_read_b128 v[46:49], v204 offset:53248
	ds_read_b128 v[54:57], v206 offset:49152
	ds_read_b128 v[58:61], v206 offset:53248
	s_waitcnt lgkmcnt(0)
	s_waitcnt lgkmcnt(7)
	v_mfma_f32_32x32x16_bf16 v[18:33], v[2:5], v[164:167], 0
	s_add_i32 s2, s60, 0xffffff66
	s_mov_b64 s[0:1], -1
	s_cmp_gt_u32 s2, 0xfffffeec
	s_waitcnt lgkmcnt(6)
	v_mfma_f32_32x32x16_bf16 v[2:17], v[6:9], v[164:167], 0
	s_waitcnt lgkmcnt(5)
	v_mfma_f32_32x32x16_bf16 v[18:33], v[34:37], v[160:163], v[18:33]
	s_waitcnt lgkmcnt(4)
	v_mfma_f32_32x32x16_bf16 v[2:17], v[38:41], v[160:163], v[2:17]
	s_waitcnt lgkmcnt(3)
	v_mfma_f32_32x32x16_bf16 v[18:33], v[42:45], v[156:159], v[18:33]
	s_waitcnt lgkmcnt(2)
	v_mfma_f32_32x32x16_bf16 v[2:17], v[46:49], v[156:159], v[2:17]
	s_waitcnt lgkmcnt(1)
	v_mfma_f32_32x32x16_bf16 v[18:33], v[54:57], v[152:155], v[18:33]
	v_lshlrev_b32_e32 v54, 2, v190
	s_waitcnt lgkmcnt(0)
	v_mfma_f32_32x32x16_bf16 v[2:17], v[58:61], v[152:155], v[2:17]
	s_cbranch_scc0 .LBB0_350
	v_sub_u32_e32 v1, 0, v54
	s_mov_b32 s0, 0x12b00
	v_add3_u32 v1, v1, v180, s0
	ds_read2_b32 v[34:35], v1 offset1:1
	ds_read2_b32 v[56:57], v1 offset0:32 offset1:33
	ds_read2_b32 v[58:59], v1 offset0:34 offset1:35
	ds_read2_b32 v[36:37], v1 offset0:2 offset1:3
	ds_read2_b32 v[38:39], v1 offset0:8 offset1:9
	ds_read2_b32 v[60:61], v1 offset0:40 offset1:41
	ds_read2_b32 v[62:63], v1 offset0:42 offset1:43
	ds_read2_b32 v[40:41], v1 offset0:10 offset1:11
	ds_read2_b32 v[42:43], v1 offset0:16 offset1:17
	ds_read2_b32 v[64:65], v1 offset0:48 offset1:49
	ds_read2_b32 v[66:67], v1 offset0:50 offset1:51
	ds_read2_b32 v[44:45], v1 offset0:18 offset1:19
	ds_read2_b32 v[46:47], v1 offset0:24 offset1:25
	ds_read2_b32 v[48:49], v1 offset0:26 offset1:27
	ds_read2_b32 v[68:69], v1 offset0:58 offset1:59
	ds_read2_b32 v[70:71], v1 offset0:56 offset1:57
	s_waitcnt lgkmcnt(3)
	v_sub_f32_e32 v47, v47, v0
	v_sub_f32_e32 v46, v46, v0
	s_waitcnt lgkmcnt(2)
	v_sub_f32_e32 v49, v49, v0
	v_sub_f32_e32 v48, v48, v0
	v_sub_f32_e32 v43, v43, v0
	v_sub_f32_e32 v42, v42, v0
	v_sub_f32_e32 v45, v45, v0
	v_sub_f32_e32 v44, v44, v0
	v_sub_f32_e32 v39, v39, v0
	v_sub_f32_e32 v38, v38, v0
	v_sub_f32_e32 v41, v41, v0
	v_sub_f32_e32 v40, v40, v0
	v_sub_f32_e32 v35, v35, v0
	v_sub_f32_e32 v34, v34, v0
	v_sub_f32_e32 v37, v37, v0
	v_sub_f32_e32 v36, v36, v0
	s_waitcnt lgkmcnt(0)
	v_sub_f32_e32 v71, v71, v0
	v_sub_f32_e32 v70, v70, v0
	v_sub_f32_e32 v69, v69, v0
	v_sub_f32_e32 v68, v68, v0
	v_sub_f32_e32 v65, v65, v0
	v_sub_f32_e32 v64, v64, v0
	v_sub_f32_e32 v67, v67, v0
	v_sub_f32_e32 v66, v66, v0
	v_sub_f32_e32 v61, v61, v0
	v_sub_f32_e32 v60, v60, v0
	v_sub_f32_e32 v63, v63, v0
	v_sub_f32_e32 v62, v62, v0
	v_sub_f32_e32 v57, v57, v0
	v_sub_f32_e32 v56, v56, v0
	v_sub_f32_e32 v59, v59, v0
	v_sub_f32_e32 v58, v58, v0
	v_pk_fma_f32 v[36:37], v[20:21], s[6:7], v[36:37] op_sel_hi:[1,0,1]
	v_pk_fma_f32 v[34:35], v[18:19], s[6:7], v[34:35] op_sel_hi:[1,0,1]
	v_pk_fma_f32 v[40:41], v[24:25], s[6:7], v[40:41] op_sel_hi:[1,0,1]
	v_pk_fma_f32 v[38:39], v[22:23], s[6:7], v[38:39] op_sel_hi:[1,0,1]
	v_pk_fma_f32 v[44:45], v[28:29], s[6:7], v[44:45] op_sel_hi:[1,0,1]
	v_pk_fma_f32 v[42:43], v[26:27], s[6:7], v[42:43] op_sel_hi:[1,0,1]
	v_pk_fma_f32 v[48:49], v[32:33], s[6:7], v[48:49] op_sel_hi:[1,0,1]
	v_pk_fma_f32 v[46:47], v[30:31], s[6:7], v[46:47] op_sel_hi:[1,0,1]
	v_pk_fma_f32 v[82:83], v[4:5], s[6:7], v[58:59] op_sel_hi:[1,0,1]
	v_pk_fma_f32 v[80:81], v[2:3], s[6:7], v[56:57] op_sel_hi:[1,0,1]
	v_pk_fma_f32 v[86:87], v[8:9], s[6:7], v[62:63] op_sel_hi:[1,0,1]
	v_pk_fma_f32 v[84:85], v[6:7], s[6:7], v[60:61] op_sel_hi:[1,0,1]
	v_pk_fma_f32 v[90:91], v[12:13], s[6:7], v[66:67] op_sel_hi:[1,0,1]
	v_pk_fma_f32 v[88:89], v[10:11], s[6:7], v[64:65] op_sel_hi:[1,0,1]
	v_pk_fma_f32 v[94:95], v[16:17], s[6:7], v[68:69] op_sel_hi:[1,0,1]
	v_pk_fma_f32 v[92:93], v[14:15], s[6:7], v[70:71] op_sel_hi:[1,0,1]
	s_mov_b64 s[0:1], 0

; #define GAS __attribute__((address_space(1)))
; template <bool GRPB> __device__ __forceinline__ void attn_pass(const float mbK, const float bmax2, const int pass, float* __restrict__ scr, bf16* __restrict__ mixrow, const float lam, const float* __restrict__ gsub, const float one_m_li, ...
;     ...
;   const float cL = __uint_as_float(__builtin_amdgcn_readfirstlane(__float_as_uint(tb2[0]))), cR = __uint_as_float(__builtin_amdgcn_readfirstlane(__float_as_uint(tb2[384])));
;   const int qw = __builtin_amdgcn_readfirstlane(q0seq + wid * 32), qpos = qw + r32;
;   float m_reg, l_reg = 0; bf16x8 qr[4]; f32x16 o[4];
; #pragma unroll
;   for (int d = 0; d < 4; ++d) o[d] = f32x16{};
;   const bf16* Qw = Qb + (long)(wid * 32 + r32) * LDK + hi * 8;
; #pragma unroll
;   for (int d0 = 0; d0 < 4; ++d0) qr[d0] = *(const GAS bf16x8*)(Qw + d0 * 16);
;     ...
;   if (pass == 0) {
; #pragma unroll
;     for (int r4 = 0; r4 < 4; ++r4) { const f32x4 lv = *(const f32x4*)(li_e + 8 * r4 + 4 * hi);
;       const f32x4 rl = (f32x4){__builtin_amdgcn_rcpf(lv[0]), __builtin_amdgcn_rcpf(lv[1]), __builtin_amdgcn_rcpf(lv[2]), __builtin_amdgcn_rcpf(lv[3])};
; #pragma unroll
;       for (int d0 = 0; d0 < 4; ++d0) scr4[d0 * 4 + r4] = (f32x4){o[d0][4 * r4 + 0] * rl[0], o[d0][4 * r4 + 1] * rl[1], o[d0][4 * r4 + 2] * rl[2], o[d0][4 * r4 + 3] * rl[3]}; }
.LBB0_373:
	s_or_b64 exec, exec, s[0:1]
	s_waitcnt lgkmcnt(0)
	v_add_u32_e32 v76, v66, v180
	ds_read_b128 v[66:69], v76
	ds_read_b128 v[70:73], v76 offset:32
	v_ashrrev_i32_e32 v147, 31, v146
	v_lshlrev_b64 v[0:1], 8, v[146:147]
	v_lshl_add_u64 v[74:75], s[40:41], 0, v[0:1]
	s_waitcnt lgkmcnt(1)
	v_rcp_f32_e32 v66, v66
	v_rcp_f32_e32 v67, v67
	v_rcp_f32_e32 v68, v68
	v_rcp_f32_e32 v69, v69
	v_mov_b32_e32 v146, v232
	v_pk_mul_f32 v[0:1], v[2:3], v[66:67]
	s_movk_i32 s0, 0xffe0
	v_pk_mul_f32 v[2:3], v[4:5], v[68:69]
	global_store_dwordx4 v[74:75], v[0:3], off
	v_mov_b32_e32 v181, v144
	s_mov_b32 s1, 0xc0000
	v_pk_mul_f32 v[0:1], v[18:19], v[66:67]
	s_waitcnt lgkmcnt(0)
	v_rcp_f32_e32 v18, v70
	v_rcp_f32_e32 v19, v71
	v_pk_mul_f32 v[2:3], v[20:21], v[68:69]
	global_store_dwordx4 v[74:75], v[0:3], off offset:64
	s_nop 1
	v_pk_mul_f32 v[0:1], v[34:35], v[66:67]
	v_pk_mul_f32 v[2:3], v[36:37], v[68:69]
	v_rcp_f32_e32 v34, v72
	v_rcp_f32_e32 v35, v73
	global_store_dwordx4 v[74:75], v[0:3], off offset:128
	s_nop 1
	v_pk_mul_f32 v[0:1], v[50:51], v[66:67]
	v_pk_mul_f32 v[2:3], v[52:53], v[68:69]
	global_store_dwordx4 v[74:75], v[0:3], off offset:192
	s_nop 1
	v_pk_mul_f32 v[0:1], v[6:7], v[18:19]
	ds_read_b128 v[4:7], v76 offset:64
	v_pk_mul_f32 v[2:3], v[8:9], v[34:35]
	global_store_dwordx4 v[74:75], v[0:3], off offset:16
	s_nop 1
	v_pk_mul_f32 v[0:1], v[22:23], v[18:19]
	v_pk_mul_f32 v[2:3], v[24:25], v[34:35]
	global_store_dwordx4 v[74:75], v[0:3], off offset:80
	s_nop 1
	v_pk_mul_f32 v[0:1], v[38:39], v[18:19]
	v_pk_mul_f32 v[2:3], v[40:41], v[34:35]
	global_store_dwordx4 v[74:75], v[0:3], off offset:144
	s_nop 1
	v_pk_mul_f32 v[0:1], v[54:55], v[18:19]
	ds_read_b128 v[18:21], v76 offset:96
	s_waitcnt lgkmcnt(1)
	v_rcp_f32_e32 v4, v4
	v_rcp_f32_e32 v5, v5
	v_rcp_f32_e32 v6, v6
	v_rcp_f32_e32 v7, v7
	v_pk_mul_f32 v[2:3], v[56:57], v[34:35]
	global_store_dwordx4 v[74:75], v[0:3], off offset:208
	s_waitcnt lgkmcnt(0)
	v_rcp_f32_e32 v8, v20
	v_rcp_f32_e32 v9, v21
	v_pk_mul_f32 v[0:1], v[10:11], v[4:5]
	v_pk_mul_f32 v[2:3], v[12:13], v[6:7]
	global_store_dwordx4 v[74:75], v[0:3], off offset:32
	s_nop 1
	v_pk_mul_f32 v[0:1], v[26:27], v[4:5]
	v_pk_mul_f32 v[2:3], v[28:29], v[6:7]
	global_store_dwordx4 v[74:75], v[0:3], off offset:96
	s_nop 1
	v_pk_mul_f32 v[0:1], v[42:43], v[4:5]
	v_pk_mul_f32 v[2:3], v[44:45], v[6:7]
	global_store_dwordx4 v[74:75], v[0:3], off offset:160
	v_mov_b32_e32 v43, v144
	s_nop 0
	v_pk_mul_f32 v[0:1], v[58:59], v[4:5]
	v_rcp_f32_e32 v4, v18
	v_rcp_f32_e32 v5, v19
	v_pk_mul_f32 v[2:3], v[60:61], v[6:7]
	global_store_dwordx4 v[74:75], v[0:3], off offset:224
	s_nop 1
	v_pk_mul_f32 v[0:1], v[14:15], v[4:5]
	v_pk_mul_f32 v[2:3], v[16:17], v[8:9]
	global_store_dwordx4 v[74:75], v[0:3], off offset:48
	s_nop 1
	v_pk_mul_f32 v[0:1], v[30:31], v[4:5]
	v_pk_mul_f32 v[2:3], v[32:33], v[8:9]
	global_store_dwordx4 v[74:75], v[0:3], off offset:112
	s_nop 1
	v_pk_mul_f32 v[0:1], v[46:47], v[4:5]
	v_pk_mul_f32 v[2:3], v[48:49], v[8:9]
	global_store_dwordx4 v[74:75], v[0:3], off offset:176
	s_nop 1
	v_pk_mul_f32 v[0:1], v[62:63], v[4:5]
	v_pk_mul_f32 v[2:3], v[64:65], v[8:9]
	global_store_dwordx4 v[74:75], v[0:3], off offset:240
	s_nop 0
	v_bfe_u32 v190, v146, 5, 1
	v_ashrrev_i32_e32 v2, 1, v146
	v_bfi_b32 v0, s0, v2, v146
	v_ashrrev_i32_e32 v1, 31, v0
	v_lshlrev_b64 v[0:1], 13, v[0:1]
	v_lshl_add_u64 v[0:1], s[52:53], 0, v[0:1]
	v_lshlrev_b32_e32 v180, 4, v190
	v_lshl_add_u64 v[0:1], v[0:1], 0, v[180:181]
	global_load_dwordx4 v[164:167], v[0:1], off offset:128
	global_load_dwordx4 v[160:163], v[0:1], off offset:160
	global_load_dwordx4 v[156:159], v[0:1], off offset:192
	v_readlane_b32 s0, v254, 39
	v_and_b32_e32 v215, 0xffffffe0, v2
	v_ashrrev_i32_e32 v36, 4, v146
	v_mov_b32_e32 v3, s0
	v_readlane_b32 s0, v254, 40
	v_lshlrev_b32_e32 v45, 3, v146
	v_ashrrev_i32_e32 v37, 31, v36
	v_mov_b32_e32 v4, s0
	ds_read_b32 v3, v3
	ds_read_b32 v4, v4
	global_load_dwordx4 v[152:155], v[0:1], off offset:224
	v_lshlrev_b64 v[48:49], 13, v[36:37]
	v_ashrrev_i32_e32 v40, 3, v146
	s_waitcnt lgkmcnt(1)
	v_readfirstlane_b32 s52, v3
	v_mov_b32_e32 v3, v144
	s_mov_b32 s0, 0x80000
	v_ashrrev_i32_e32 v41, 31, v40
	v_lshlrev_b32_e32 v46, 4, v146
	v_lshlrev_b64 v[50:51], 13, v[40:41]
	v_add_u32_e32 v38, 32, v36
	v_and_b32_e32 v42, 0x70, v46
	v_lshl_add_u64 v[8:9], s[50:51], 0, v[50:51]
	v_ashrrev_i32_e32 v39, 31, v38
	v_lshl_add_u64 v[32:33], v[8:9], 0, v[42:43]
	s_waitcnt lgkmcnt(0)
	v_readfirstlane_b32 s53, v4
	s_barrier
; __device__ __forceinline__ float bf2f(unsigned short b) { return __uint_as_float(((unsigned)b) << 16); }
; __device__ __forceinline__ int v_st(int k, int c) { const int kk = (k & ~0xC) | ((k & 4) << 1) | ((k & 8) >> 1); return ((kk >> 3) * 4 + (c >> 5)) * 512 + ((kk & 7) * 32 + (c & 31)) * 2; }
; __device__ __forceinline__ int v_rd_base(int lane) { return ((lane & 3) << 3) | (((lane >> 2) & 3) << 6) | (((lane >> 4) & 1) << 5) | (((lane >> 5) & 1) << 8); }
; #define SLOAD(i, k0) do { sr_[i].vs0 = *(const GAS bf16x8*)(&Vh[(long)((k0) + sr) * LDK + sc]); sr_[i].vs1 = *(const GAS bf16x8*)(&Vh[(long)((k0) + 32 + sr) * LDK + sc]); \
;     sr_[i].ks0 = *(const GAS bf16x8*)(&Kh[(long)((k0) + kr) * LDK + kc]); } while (0)
; #define SWRITE(b, i) do { *(bf16x8*)(V_lds + (b) * SHM_V + vst0) = sr_[i].vs0; *(bf16x8*)(V_lds + (b) * SHM_V + vst1) = sr_[i].vs1; \
;     *(bf16x8*)(K_lds + (b) * SHM_K + kst) = sr_[i].ks0; } while (0)
; template <bool GRPB> __device__ __forceinline__ void attn_pass(const float mbK, const float bmax2, const int pass, float* __restrict__ scr, bf16* __restrict__ mixrow, const float lam, const float* __restrict__ gsub, const float one_m_li, ...
;     ...
;   { float qs = 0.f;
; #pragma unroll
;     for (int d0 = 0; d0 < 4; ++d0)
; #pragma unroll
;       for (int j = 0; j < 8; ++j) { const float v = bf2f((unsigned short)qr[d0][j]); qs = fmaf(v, v, qs); }
;     { auto rr = __builtin_amdgcn_permlane32_swap(__float_as_uint(qs), __float_as_uint(qs), false, false); qs = __uint_as_float(rr[0]) + __uint_as_float(rr[1]); }
;     m_reg = __builtin_sqrtf(qs) * mbK + bmax2 + 0.25f; }
;   const int sr = tid >> 4, sc = (tid & 15) * 8, vst0 = v_st(sr, sc), vst1 = v_st(32 + sr, sc);
;   const int kr = tid >> 3, kc = (tid & 7) * 8, kst = KSWZ64(kr, kc * 2);
;   const int vb0 = (int)(uintptr_t)V_lds + v_rd_base(lane);
;   struct { bf16x8 vs0, vs1, ks0; } sr_[2];
;     ...
;   f32x16 pA0, pA1, pB0, pB1; float mnA, mnB, alA, alB; bf16x8 pa0, pa1, pa2, pa3; constexpr int NT = SEQ / KVBLK;
;   __syncthreads();
;   SLOAD(0, 0); SLOAD(1, KVBLK); asm volatile("s_waitcnt vmcnt(0)" ::: "memory"); SWRITE(0, 0); SWRITE(1, 1);
;   SLOAD(0, 2 * KVBLK); asm volatile("s_waitcnt vmcnt(0)" ::: "memory"); SWRITE(2, 0); __syncthreads();
	v_add_u32_e32 v41, s39, v215
	v_and_b32_e32 v181, 31, v146
	v_readfirstlane_b32 s39, v41
	s_waitcnt vmcnt(3)
	v_lshlrev_b32_e32 v0, 16, v164
	v_and_b32_e32 v1, 0xffff0000, v164
	v_fma_f32 v44, v0, v0, 0
	v_lshlrev_b32_e32 v2, 16, v165
	v_fmac_f32_e32 v44, v1, v1
	v_fmac_f32_e32 v44, v2, v2
	v_and_b32_e32 v0, 0xffff0000, v165
	v_fmac_f32_e32 v44, v0, v0
	v_lshlrev_b32_e32 v0, 16, v166
	v_fmac_f32_e32 v44, v0, v0
	v_and_b32_e32 v0, 0xffff0000, v166
	v_fmac_f32_e32 v44, v0, v0
	v_lshlrev_b32_e32 v0, 16, v167
	v_fmac_f32_e32 v44, v0, v0
	v_and_b32_e32 v0, 0xffff0000, v167
	v_fmac_f32_e32 v44, v0, v0
	s_waitcnt vmcnt(2)
	v_lshlrev_b32_e32 v0, 16, v160
	v_fmac_f32_e32 v44, v0, v0
	v_and_b32_e32 v0, 0xffff0000, v160
	v_fmac_f32_e32 v44, v0, v0
	v_lshlrev_b32_e32 v0, 16, v161
	v_fmac_f32_e32 v44, v0, v0
	v_and_b32_e32 v0, 0xffff0000, v161
	v_fmac_f32_e32 v44, v0, v0
	v_lshlrev_b32_e32 v0, 16, v162
	v_fmac_f32_e32 v44, v0, v0
	v_and_b32_e32 v0, 0xffff0000, v162
	v_fmac_f32_e32 v44, v0, v0
	v_lshlrev_b32_e32 v0, 16, v163
	v_fmac_f32_e32 v44, v0, v0
	v_and_b32_e32 v0, 0xffff0000, v163
	v_fmac_f32_e32 v44, v0, v0
	s_waitcnt vmcnt(1)
	v_lshlrev_b32_e32 v0, 16, v156
	v_fmac_f32_e32 v44, v0, v0
	v_and_b32_e32 v0, 0xffff0000, v156
	v_fmac_f32_e32 v44, v0, v0
	v_lshlrev_b32_e32 v0, 16, v157
	v_fmac_f32_e32 v44, v0, v0
	v_and_b32_e32 v0, 0xffff0000, v157
	v_fmac_f32_e32 v44, v0, v0
	v_lshlrev_b32_e32 v0, 16, v158
	v_fmac_f32_e32 v44, v0, v0
	v_and_b32_e32 v0, 0xffff0000, v158
	v_fmac_f32_e32 v44, v0, v0
	v_lshlrev_b32_e32 v0, 16, v159
	v_and_b32_e32 v2, 0x78, v45
	v_fmac_f32_e32 v44, v0, v0
	v_lshl_add_u64 v[0:1], s[50:51], 0, v[48:49]
	v_lshlrev_b32_e32 v2, 1, v2
	v_lshl_add_u64 v[24:25], v[0:1], 0, v[2:3]
	v_add_co_u32_e32 v12, vcc, s0, v24
	v_lshlrev_b64 v[0:1], 13, v[38:39]
	s_nop 0
	v_addc_co_u32_e32 v13, vcc, 0, v25, vcc
	v_add_co_u32_e32 v16, vcc, s1, v24
	v_lshl_add_u64 v[0:1], s[50:51], 0, v[0:1]
	s_nop 0
	v_addc_co_u32_e32 v17, vcc, 0, v25, vcc
	v_add_co_u32_e32 v20, vcc, s0, v32
	s_mov_b32 s0, 0x100000
	s_nop 0
	v_addc_co_u32_e32 v21, vcc, 0, v33, vcc
	v_lshl_add_u64 v[4:5], v[0:1], 0, v[2:3]
	v_add_co_u32_e32 v26, vcc, s0, v24
	global_load_dwordx4 v[0:3], v[24:25], off offset:2048
	s_nop 0
	global_load_dwordx4 v[4:7], v[4:5], off offset:2048
	s_nop 0
	global_load_dwordx4 v[8:11], v[32:33], off offset:1152
	s_nop 0
	global_load_dwordx4 v[12:15], v[12:13], off offset:2048
	s_nop 0
	global_load_dwordx4 v[16:19], v[16:17], off offset:2048
	s_nop 0
	global_load_dwordx4 v[20:23], v[20:21], off offset:1152
	v_addc_co_u32_e32 v27, vcc, 0, v25, vcc
	s_mov_b32 s1, 0x140000
	v_add_co_u32_e32 v28, vcc, s1, v24
	s_waitcnt vmcnt(0)
	v_and_b32_e32 v37, 0xffff0000, v159
	s_nop 0
	v_addc_co_u32_e32 v29, vcc, 0, v25, vcc
	v_add_co_u32_e32 v32, vcc, s0, v32
	global_load_dwordx4 v[24:27], v[26:27], off offset:2048
	s_nop 0
	global_load_dwordx4 v[28:31], v[28:29], off offset:2048
	v_addc_co_u32_e32 v33, vcc, 0, v33, vcc
	global_load_dwordx4 v[32:35], v[32:33], off offset:1152
	v_fmac_f32_e32 v44, v37, v37
	s_waitcnt vmcnt(9)
	v_lshlrev_b32_e32 v37, 16, v152
	v_fmac_f32_e32 v44, v37, v37
	v_and_b32_e32 v37, 0xffff0000, v152
	v_fmac_f32_e32 v44, v37, v37
	v_lshlrev_b32_e32 v37, 16, v153
	v_fmac_f32_e32 v44, v37, v37
	v_and_b32_e32 v37, 0xffff0000, v153
	v_fmac_f32_e32 v44, v37, v37
	v_lshlrev_b32_e32 v37, 16, v154
	v_fmac_f32_e32 v44, v37, v37
	v_and_b32_e32 v37, 0xffff0000, v154
	v_fmac_f32_e32 v44, v37, v37
	v_lshlrev_b32_e32 v37, 16, v155
	v_fmac_f32_e32 v44, v37, v37
	v_and_b32_e32 v37, 0xffff0000, v155
	v_fmac_f32_e32 v44, v37, v37
	v_mov_b32_e32 v37, v44
	s_nop 1
	v_permlane32_swap_b32_e32 v44, v37
	v_add_f32_e32 v37, v44, v37
	v_mul_f32_e32 v39, 0x4f800000, v37
	v_cmp_gt_f32_e32 vcc, s10, v37
	v_add_u32_e32 v192, s39, v181
	s_nop 0
	v_cndmask_b32_e32 v37, v37, v39, vcc
	v_sqrt_f32_e32 v39, v37
	s_nop 0
	v_add_u32_e32 v41, -1, v39
	v_fma_f32 v43, -v41, v39, v37
	v_cmp_ge_f32_e64 s[0:1], 0, v43
	v_add_u32_e32 v43, 1, v39
	s_nop 0
	v_cndmask_b32_e64 v41, v39, v41, s[0:1]
	v_fma_f32 v39, -v43, v39, v37
	v_cmp_lt_f32_e64 s[0:1], 0, v39
	s_nop 1
	v_cndmask_b32_e64 v39, v41, v43, s[0:1]
	v_mul_f32_e32 v41, 0x37800000, v39
	v_cndmask_b32_e32 v39, v39, v41, vcc
	v_cmp_class_f32_e32 vcc, v37, v198
	v_bfe_u32 v41, v45, 5, 2
	s_nop 0
	v_cndmask_b32_e32 v37, v39, v37, vcc
	v_fma_f32 v37, v214, v37, s45
	v_add_f32_e32 v64, 0x3e800000, v37
	v_and_b32_e32 v37, 0xfffff0, v36
	v_lshlrev_b32_e32 v39, 1, v36
	v_and_or_b32 v37, v39, 8, v37
	v_lshrrev_b32_e32 v39, 1, v36
	v_lshrrev_b32_e32 v37, 1, v37
	v_and_b32_e32 v36, 3, v36
	v_or_b32_e32 v37, v37, v41
	v_and_or_b32 v36, v39, 4, v36
	v_lshlrev_b32_e32 v37, 9, v37
	v_lshlrev_b32_e32 v36, 6, v36
	v_and_b32_e32 v39, 48, v46
	v_or3_b32 v193, v37, v36, v39
	v_and_b32_e32 v37, 0xfffff0, v38
	v_lshlrev_b32_e32 v38, 1, v38
	v_and_or_b32 v37, v38, 8, v37
	v_lshrrev_b32_e32 v37, 1, v37
	v_or_b32_e32 v37, v37, v41
	v_lshlrev_b32_e32 v37, 9, v37
	v_or3_b32 v194, v37, v36, v39
	v_lshlrev_b32_e32 v36, 7, v40
	v_and_b32_e32 v37, 0x70, v146
	v_bitop3_b32 v195, v42, v36, v37 bitop3:0xde
	v_add_u32_e32 v36, 0, v193
	s_waitcnt vmcnt(8)
	ds_write_b128 v36, v[0:3]
	v_add_u32_e32 v0, 0, v194
	v_add_u32_e32 v200, 0, v195
	s_waitcnt vmcnt(7)
	ds_write_b128 v0, v[4:7]
	s_waitcnt vmcnt(6)
	ds_write_b128 v200, v[8:11] offset:49152
	s_waitcnt vmcnt(5)
	ds_write_b128 v36, v[12:15] offset:16384
	s_waitcnt vmcnt(4)
	ds_write_b128 v0, v[16:19] offset:16384
	s_waitcnt vmcnt(3)
	ds_write_b128 v200, v[20:23] offset:57344
	v_lshlrev_b32_e32 v8, 7, v181
	v_and_b32_e32 v9, 0x70, v45
	v_or_b32_e32 v10, 32, v180
	v_bitop3_b32 v206, v10, v8, v9 bitop3:0xde
	v_or_b32_e32 v10, 64, v180
	v_bitop3_b32 v208, v10, v8, v9 bitop3:0xde
	v_or_b32_e32 v10, 0x60, v180
	v_bitop3_b32 v203, v180, v8, v9 bitop3:0xde
	v_bitop3_b32 v209, v10, v8, v9 bitop3:0xde
	s_waitcnt vmcnt(2)
	ds_write_b128 v36, v[24:27] offset:32768
	s_waitcnt vmcnt(1)
	ds_write_b128 v0, v[28:31] offset:32768
	v_add_u32_e32 v0, 0x10000, v200
	v_add_u32_e32 v202, 0, v203
	v_add_u32_e32 v204, 0, v206
	v_add_u32_e32 v205, 0, v208
	v_add_u32_e32 v207, 0, v209
	s_waitcnt vmcnt(0)
	ds_write_b128 v0, v[32:35]
	s_waitcnt lgkmcnt(0)
	s_barrier
; #define SBAR() __builtin_amdgcn_sched_barrier(0)
; __device__ __forceinline__ void partialSM(f32x16& p0, f32x16& p1, float& m_reg, float& mn, float& alpha, int kt0, int qpos, int qw, int hi, const float* tb2, float cL, float cR) {
;   mn = m_reg; alpha = 1.f;
;   const int rel_hi = kt0 + 63 - qw, rel_lo = kt0 - (qw + 31);
;   if (rel_hi <= -91 || rel_lo >= 91) {
;     const float cm = ((rel_hi <= -91) ? cL : cR) - m_reg;
; #pragma unroll
;     for (int r = 0; r < 16; ++r) { p0[r] = fmaf(p0[r], C1, cm); p1[r] = fmaf(p1[r], C1, cm); }
;   } else {
;     const float* tp = tb2 + (kt0 - qpos + 192 + 4 * hi);
; #pragma unroll
;     for (int r4 = 0; r4 < 4; ++r4) {
;       float ta[4], tb[4];
; #pragma unroll
;       for (int i = 0; i < 4; ++i) { ta[i] = tp[8 * r4 + i] - m_reg; tb[i] = tp[32 + 8 * r4 + i] - m_reg; }
; #pragma unroll
;       for (int i = 0; i < 4; ++i) { p0[4 * r4 + i] = fmaf(p0[4 * r4 + i], C1, ta[i]); p1[4 * r4 + i] = fmaf(p1[4 * r4 + i], C1, tb[i]); }
;       asm volatile("" ::: "memory");
;     }
; __device__ __forceinline__ void qkt(f32x16& p0, f32x16& p1, const char* Ks, const bf16x8* qr, int r32, int hi) {
;   bf16x8 ka[4], kb[4];
; #pragma unroll
;   for (int d0 = 0; d0 < 4; ++d0) { const int cb = (d0 * 16 + hi * 8) * 2;
;     ka[d0] = *reinterpret_cast<const bf16x8*>(Ks + KSWZ64(r32, cb)); kb[d0] = *reinterpret_cast<const bf16x8*>(Ks + KSWZ64(32 + r32, cb)); }
;   asm volatile("s_waitcnt lgkmcnt(0)" ::: "memory"); SBAR();
;   p0 = f32x16{}; p1 = f32x16{};
; #pragma unroll
;   for (int d0 = 0; d0 < 4; ++d0) {
;     p0 = __builtin_amdgcn_mfma_f32_32x32x16_bf16(ka[d0], qr[d0], p0, 0, 0, 0);
;     p1 = __builtin_amdgcn_mfma_f32_32x32x16_bf16(kb[d0], qr[d0], p1, 0, 0, 0); }
	ds_read_b128 v[0:3], v202 offset:49152
	ds_read_b128 v[4:7], v202 offset:53248
	ds_read_b128 v[32:35], v204 offset:49152
	ds_read_b128 v[36:39], v204 offset:53248
	ds_read_b128 v[40:43], v205 offset:49152
	ds_read_b128 v[44:47], v205 offset:53248
	ds_read_b128 v[52:55], v207 offset:49152
	ds_read_b128 v[56:59], v207 offset:53248
	s_waitcnt lgkmcnt(0)
	s_waitcnt lgkmcnt(7)
	v_mfma_f32_32x32x16_bf16 v[16:31], v[0:3], v[164:167], 0
	s_add_i32 s4, s39, 0xffffff66
	s_mov_b64 s[0:1], -1
	s_cmp_gt_u32 s4, 0xfffffeec
	s_waitcnt lgkmcnt(6)
	v_mfma_f32_32x32x16_bf16 v[0:15], v[4:7], v[164:167], 0
	s_waitcnt lgkmcnt(5)
	v_mfma_f32_32x32x16_bf16 v[16:31], v[32:35], v[160:163], v[16:31]
	s_waitcnt lgkmcnt(4)
	v_mfma_f32_32x32x16_bf16 v[0:15], v[36:39], v[160:163], v[0:15]
	s_waitcnt lgkmcnt(3)
	v_mfma_f32_32x32x16_bf16 v[16:31], v[40:43], v[156:159], v[16:31]
	s_waitcnt lgkmcnt(2)
	v_mfma_f32_32x32x16_bf16 v[0:15], v[44:47], v[156:159], v[0:15]
	s_waitcnt lgkmcnt(1)
	v_mfma_f32_32x32x16_bf16 v[16:31], v[52:55], v[152:155], v[16:31]
	v_lshlrev_b32_e32 v52, 2, v192
	s_waitcnt lgkmcnt(0)
	v_mfma_f32_32x32x16_bf16 v[0:15], v[56:59], v[152:155], v[0:15]
	s_cbranch_scc0 .LBB0_375
	v_sub_u32_e32 v32, 0, v52
	s_mov_b32 s0, 0x12b00
	v_add3_u32 v53, v32, v180, s0
	ds_read2_b32 v[32:33], v53 offset1:1
	ds_read2_b32 v[54:55], v53 offset0:32 offset1:33
	ds_read2_b32 v[56:57], v53 offset0:34 offset1:35
	ds_read2_b32 v[34:35], v53 offset0:2 offset1:3
	ds_read2_b32 v[36:37], v53 offset0:8 offset1:9
	ds_read2_b32 v[58:59], v53 offset0:40 offset1:41
	ds_read2_b32 v[60:61], v53 offset0:42 offset1:43
	ds_read2_b32 v[38:39], v53 offset0:10 offset1:11
	ds_read2_b32 v[40:41], v53 offset0:16 offset1:17
	ds_read2_b32 v[62:63], v53 offset0:48 offset1:49
	ds_read2_b32 v[66:67], v53 offset0:50 offset1:51
	ds_read2_b32 v[42:43], v53 offset0:18 offset1:19
	ds_read2_b32 v[44:45], v53 offset0:24 offset1:25
	ds_read2_b32 v[46:47], v53 offset0:26 offset1:27
	ds_read2_b32 v[68:69], v53 offset0:58 offset1:59
	ds_read2_b32 v[70:71], v53 offset0:56 offset1:57
	s_waitcnt lgkmcnt(3)
	v_sub_f32_e32 v45, v45, v64
	v_sub_f32_e32 v44, v44, v64
	s_waitcnt lgkmcnt(2)
	v_sub_f32_e32 v47, v47, v64
	v_sub_f32_e32 v46, v46, v64
	v_sub_f32_e32 v41, v41, v64
	v_sub_f32_e32 v40, v40, v64
	v_sub_f32_e32 v43, v43, v64
	v_sub_f32_e32 v42, v42, v64
	v_sub_f32_e32 v37, v37, v64
	v_sub_f32_e32 v36, v36, v64
	v_sub_f32_e32 v39, v39, v64
	v_sub_f32_e32 v38, v38, v64
	v_sub_f32_e32 v33, v33, v64
	v_sub_f32_e32 v32, v32, v64
	v_sub_f32_e32 v35, v35, v64
	v_sub_f32_e32 v34, v34, v64
	s_waitcnt lgkmcnt(0)
	v_sub_f32_e32 v71, v71, v64
	v_sub_f32_e32 v70, v70, v64
	v_sub_f32_e32 v69, v69, v64
	v_sub_f32_e32 v68, v68, v64
	v_sub_f32_e32 v63, v63, v64
	v_sub_f32_e32 v62, v62, v64
	v_sub_f32_e32 v67, v67, v64
	v_sub_f32_e32 v66, v66, v64
	v_sub_f32_e32 v59, v59, v64
	v_sub_f32_e32 v58, v58, v64
	v_sub_f32_e32 v61, v61, v64
	v_sub_f32_e32 v60, v60, v64
	v_sub_f32_e32 v55, v55, v64
	v_sub_f32_e32 v54, v54, v64
	v_sub_f32_e32 v57, v57, v64
	v_sub_f32_e32 v56, v56, v64
	v_pk_fma_f32 v[34:35], v[18:19], s[6:7], v[34:35] op_sel_hi:[1,0,1]
	v_pk_fma_f32 v[32:33], v[16:17], s[6:7], v[32:33] op_sel_hi:[1,0,1]
	v_pk_fma_f32 v[38:39], v[22:23], s[6:7], v[38:39] op_sel_hi:[1,0,1]
	v_pk_fma_f32 v[36:37], v[20:21], s[6:7], v[36:37] op_sel_hi:[1,0,1]
	v_pk_fma_f32 v[42:43], v[26:27], s[6:7], v[42:43] op_sel_hi:[1,0,1]
	v_pk_fma_f32 v[40:41], v[24:25], s[6:7], v[40:41] op_sel_hi:[1,0,1]
	v_pk_fma_f32 v[46:47], v[30:31], s[6:7], v[46:47] op_sel_hi:[1,0,1]
	v_pk_fma_f32 v[44:45], v[28:29], s[6:7], v[44:45] op_sel_hi:[1,0,1]
	v_pk_fma_f32 v[82:83], v[2:3], s[6:7], v[56:57] op_sel_hi:[1,0,1]
	v_pk_fma_f32 v[80:81], v[0:1], s[6:7], v[54:55] op_sel_hi:[1,0,1]
	v_pk_fma_f32 v[86:87], v[6:7], s[6:7], v[60:61] op_sel_hi:[1,0,1]
	v_pk_fma_f32 v[84:85], v[4:5], s[6:7], v[58:59] op_sel_hi:[1,0,1]
	v_pk_fma_f32 v[90:91], v[10:11], s[6:7], v[66:67] op_sel_hi:[1,0,1]
	v_pk_fma_f32 v[88:89], v[8:9], s[6:7], v[62:63] op_sel_hi:[1,0,1]
	v_pk_fma_f32 v[94:95], v[14:15], s[6:7], v[68:69] op_sel_hi:[1,0,1]
	v_pk_fma_f32 v[92:93], v[12:13], s[6:7], v[70:71] op_sel_hi:[1,0,1]
	s_mov_b64 s[0:1], 0
